# GEMM main loops: per-phase s_setprio flips removed (A/B'd: up-projection GEMM ~2% faster without them)
# speedup vs baseline: 1.0140x; 1.0140x over previous
; #define PG8_STAGE(bufoff, gbase, voff) do { _Pragma("unroll") for (int _i = 0; _i < 2; ++_i) \
;         __builtin_amdgcn_global_load_lds((const unsigned*)((const char*)(gbase) + (voff)[_i]), (PG8_LAS unsigned*)(lds + (bufoff) + ldsw + _i * 8192), 16, 0, 0); } while (0)
; #define PG8_LDA(dst, b, h) do { _Pragma("unroll") for (int m = 0; m < 4; ++m) _Pragma("unroll") for (int k = 0; k < 2; ++k) dst[m][k] = *(const PG8_LAS bf16x8*)(lds + PG8_SA(b, h) + aoff + m * 2048 + k * 1024); } while (0)
; #define PG8_LDB(dst, b, h) do { _Pragma("unroll") for (int n = 0; n < 2; ++n) _Pragma("unroll") for (int k = 0; k < 2; ++k) dst[n][k] = *(const PG8_LAS bf16x8*)(lds + PG8_SB(b, h) + boff + n * 2048 + k * 1024); } while (0)
; #define PG8_MMA(ai, bj, At, Bt) do { __builtin_amdgcn_s_setprio(1); _Pragma("unroll") for (int m = 0; m < 4; ++m) _Pragma("unroll") for (int n = 0; n < 2; ++n) _Pragma("unroll") for (int k = 0; k < 2; ++k) \
;         acc[ai][bj][m][n] = __builtin_amdgcn_mfma_f32_16x16x32_bf16(Bt[n][k], At[m][k], acc[ai][bj][m][n], 0, 0, 0); __builtin_amdgcn_s_setprio(0); } while (0)
; #define PG8_WAIT_V(n) asm volatile("s_waitcnt vmcnt(" #n ")" ::: "memory")
; template <class Epi, class Sched>
; __device__ __forceinline__ void gemm_phase(PG8_LAS unsigned char* lds, const Gemm g, const Sched& S, const Epi& E) {
;     ...
;         for (int t = 0; t < nt; t += 2) {
;             const bool last = (t == nt - 2);
;             const char* a1 = cA + (size_t)(t + 1) * kstep;
;             const char* a2 = last ? nA : cA + (size_t)(t + 2) * kstep; const char* b2 = last ? nB : cB + (size_t)(t + 2) * kstep;
;             const char* a3 = a2 + kstep; const char* b3 = b2 + kstep;
;             if (last && has_next) S.a_ready(nxt);
;             PG8_LDB(B0, 0, 0); PG8_SCHED; PG8_LDA(At, 0, 0); PG8_STAGE(PG8_SA(1, 1), a1 + hstep, voffA);
;             PG8_WAIT_L(8); PG8_BAR; PG8_WAIT_L(0); PG8_MMA(0, 0, At, B0); PG8_BAR; PG8_SCHED;
;             PG8_LDB(B1, 0, 1); PG8_STAGE(PG8_SB(0, 0), b2, voffB);
;             PG8_BAR; PG8_WAIT_L(0); PG8_MMA(0, 1, At, B1); PG8_BAR;
;             PG8_LDA(At, 0, 1); PG8_STAGE(PG8_SA(0, 0), a2, voffA);
;             PG8_BAR; PG8_WAIT_L(0); PG8_MMA(1, 0, At, B0); PG8_BAR; PG8_SCHED;
;             PG8_STAGE(PG8_SB(0, 1), b2 + hstep, voffB);
;             PG8_WAIT_V(6); PG8_BAR; PG8_MMA(1, 1, At, B1); PG8_BAR;
.LBB0_1071:
	s_add_u32 s20, s18, 0xfffc0080
	s_addc_u32 s21, s19, -1
	s_add_i32 s51, 0, 0x10000
	v_add_u32_e32 v144, s51, v147
	ds_read_b128 v[150:153], v144
	ds_read_b128 v[154:157], v144 offset:1024
	ds_read_b128 v[176:179], v144 offset:2048
	ds_read_b128 v[180:183], v144 offset:3072
	s_cmp_eq_u32 s50, 12
	s_cselect_b32 s23, s13, s21
	s_cselect_b32 s22, s40, s20
	s_cselect_b32 s21, s11, s45
	s_cselect_b32 s20, s41, s44
	v_lshl_add_u64 v[144:145], s[18:19], 0, v[140:141]
	s_add_i32 m0, s29, 0xc000
	ds_read_b128 v[184:187], v149
	ds_read_b128 v[188:191], v149 offset:1024
	ds_read_b128 v[192:195], v149 offset:2048
	ds_read_b128 v[196:199], v149 offset:3072
	ds_read_b128 v[200:203], v149 offset:4096
	ds_read_b128 v[204:207], v149 offset:5120
	ds_read_b128 v[208:211], v149 offset:6144
	ds_read_b128 v[212:215], v149 offset:7168
	global_load_lds_dwordx4 v[144:145], off
	v_lshl_add_u64 v[144:145], s[18:19], 0, v[142:143]
	s_add_i32 m0, s29, 0xe000
	s_nop 0
	global_load_lds_dwordx4 v[144:145], off
	s_waitcnt lgkmcnt(8)
	s_barrier
	s_waitcnt lgkmcnt(0)
	s_waitcnt lgkmcnt(0)
	v_mfma_f32_16x16x32_bf16 v[126:129], v[150:153], v[184:187], v[126:129]
	v_mfma_f32_16x16x32_bf16 v[122:125], v[176:179], v[184:187], v[122:125]
	v_mfma_f32_16x16x32_bf16 v[118:121], v[150:153], v[192:195], v[118:121]
	v_mfma_f32_16x16x32_bf16 v[110:113], v[176:179], v[192:195], v[110:113]
	v_mfma_f32_16x16x32_bf16 v[102:105], v[150:153], v[200:203], v[102:105]
	v_mfma_f32_16x16x32_bf16 v[94:97], v[176:179], v[200:203], v[94:97]
	v_mfma_f32_16x16x32_bf16 v[86:89], v[150:153], v[208:211], v[86:89]
	v_mfma_f32_16x16x32_bf16 v[78:81], v[176:179], v[208:211], v[78:81]
	v_mfma_f32_16x16x32_bf16 v[126:129], v[154:157], v[188:191], v[126:129]
	v_mfma_f32_16x16x32_bf16 v[122:125], v[180:183], v[188:191], v[122:125]
	v_mfma_f32_16x16x32_bf16 v[118:121], v[154:157], v[196:199], v[118:121]
	v_mfma_f32_16x16x32_bf16 v[110:113], v[180:183], v[196:199], v[110:113]
	v_mfma_f32_16x16x32_bf16 v[102:105], v[154:157], v[204:207], v[102:105]
	v_mfma_f32_16x16x32_bf16 v[94:97], v[180:183], v[204:207], v[94:97]
	v_mfma_f32_16x16x32_bf16 v[86:89], v[154:157], v[212:215], v[86:89]
	v_mfma_f32_16x16x32_bf16 v[78:81], v[180:183], v[212:215], v[78:81]
	s_barrier
	s_add_i32 s59, 0, 0x14000
	v_add_u32_e32 v144, s59, v147
	s_add_i32 s51, s51, s28
	ds_read_b128 v[216:219], v144
	ds_read_b128 v[220:223], v144 offset:1024
	ds_read_b128 v[224:227], v144 offset:2048
	ds_read_b128 v[228:231], v144 offset:3072
	v_lshl_add_u64 v[144:145], s[20:21], 0, v[0:1]
	s_mov_b32 m0, s51
	v_lshl_add_u64 v[158:159], s[20:21], 0, v[134:135]
	global_load_lds_dwordx4 v[144:145], off
	s_add_i32 m0, s51, 0x2000
	s_nop 0
	global_load_lds_dwordx4 v[158:159], off
	s_barrier
	s_waitcnt lgkmcnt(0)
	s_waitcnt lgkmcnt(0)
	v_mfma_f32_16x16x32_bf16 v[114:117], v[216:219], v[184:187], v[114:117]
	v_mfma_f32_16x16x32_bf16 v[106:109], v[224:227], v[184:187], v[106:109]
	v_mfma_f32_16x16x32_bf16 v[98:101], v[216:219], v[192:195], v[98:101]
	v_mfma_f32_16x16x32_bf16 v[90:93], v[224:227], v[192:195], v[90:93]
	v_mfma_f32_16x16x32_bf16 v[82:85], v[216:219], v[200:203], v[82:85]
	v_mfma_f32_16x16x32_bf16 v[74:77], v[224:227], v[200:203], v[74:77]
	v_mfma_f32_16x16x32_bf16 v[70:73], v[216:219], v[208:211], v[70:73]
	v_mfma_f32_16x16x32_bf16 v[66:69], v[224:227], v[208:211], v[66:69]
	v_mfma_f32_16x16x32_bf16 v[114:117], v[220:223], v[188:191], v[114:117]
	v_mfma_f32_16x16x32_bf16 v[106:109], v[228:231], v[188:191], v[106:109]
	v_mfma_f32_16x16x32_bf16 v[98:101], v[220:223], v[196:199], v[98:101]
	v_mfma_f32_16x16x32_bf16 v[90:93], v[228:231], v[196:199], v[90:93]
	v_mfma_f32_16x16x32_bf16 v[82:85], v[220:223], v[204:207], v[82:85]
	v_mfma_f32_16x16x32_bf16 v[74:77], v[228:231], v[204:207], v[74:77]
	v_mfma_f32_16x16x32_bf16 v[70:73], v[220:223], v[212:215], v[70:73]
	v_mfma_f32_16x16x32_bf16 v[66:69], v[228:231], v[212:215], v[66:69]
	s_mov_b32 m0, s29
	v_lshl_add_u64 v[232:233], s[22:23], 0, v[138:139]
	s_barrier
	ds_read_b128 v[184:187], v149 offset:16384
	ds_read_b128 v[188:191], v149 offset:17408
	ds_read_b128 v[192:195], v149 offset:18432
	ds_read_b128 v[196:199], v149 offset:19456
	ds_read_b128 v[200:203], v149 offset:20480
	ds_read_b128 v[204:207], v149 offset:21504
	ds_read_b128 v[208:211], v149 offset:22528
	ds_read_b128 v[212:215], v149 offset:23552
	global_load_lds_dwordx4 v[232:233], off
	v_lshl_add_u64 v[234:235], s[22:23], 0, v[136:137]
	s_mov_b32 m0, s30
	s_nop 0
	global_load_lds_dwordx4 v[234:235], off
	s_barrier
	s_waitcnt lgkmcnt(0)
	s_waitcnt lgkmcnt(0)
	v_mfma_f32_16x16x32_bf16 v[62:65], v[150:153], v[184:187], v[62:65]
	v_mfma_f32_16x16x32_bf16 v[58:61], v[176:179], v[184:187], v[58:61]
	v_mfma_f32_16x16x32_bf16 v[50:53], v[150:153], v[192:195], v[50:53]
	v_mfma_f32_16x16x32_bf16 v[42:45], v[176:179], v[192:195], v[42:45]
	v_mfma_f32_16x16x32_bf16 v[34:37], v[150:153], v[200:203], v[34:37]
	v_mfma_f32_16x16x32_bf16 v[26:29], v[176:179], v[200:203], v[26:29]
	v_mfma_f32_16x16x32_bf16 v[18:21], v[150:153], v[208:211], v[18:21]
	v_mfma_f32_16x16x32_bf16 v[10:13], v[176:179], v[208:211], v[10:13]
	v_mfma_f32_16x16x32_bf16 v[62:65], v[154:157], v[188:191], v[62:65]
	v_mfma_f32_16x16x32_bf16 v[58:61], v[180:183], v[188:191], v[58:61]
	v_mfma_f32_16x16x32_bf16 v[50:53], v[154:157], v[196:199], v[50:53]
	v_mfma_f32_16x16x32_bf16 v[42:45], v[180:183], v[196:199], v[42:45]
	v_mfma_f32_16x16x32_bf16 v[34:37], v[154:157], v[204:207], v[34:37]
	v_mfma_f32_16x16x32_bf16 v[26:29], v[180:183], v[204:207], v[26:29]
	v_mfma_f32_16x16x32_bf16 v[18:21], v[154:157], v[212:215], v[18:21]
	v_mfma_f32_16x16x32_bf16 v[10:13], v[180:183], v[212:215], v[10:13]
	s_barrier
; #define PG8_STAGE(bufoff, gbase, voff) do { _Pragma("unroll") for (int _i = 0; _i < 2; ++_i) \
;         __builtin_amdgcn_global_load_lds((const unsigned*)((const char*)(gbase) + (voff)[_i]), (PG8_LAS unsigned*)(lds + (bufoff) + ldsw + _i * 8192), 16, 0, 0); } while (0)
; #define PG8_LDA(dst, b, h) do { _Pragma("unroll") for (int m = 0; m < 4; ++m) _Pragma("unroll") for (int k = 0; k < 2; ++k) dst[m][k] = *(const PG8_LAS bf16x8*)(lds + PG8_SA(b, h) + aoff + m * 2048 + k * 1024); } while (0)
; #define PG8_LDB(dst, b, h) do { _Pragma("unroll") for (int n = 0; n < 2; ++n) _Pragma("unroll") for (int k = 0; k < 2; ++k) dst[n][k] = *(const PG8_LAS bf16x8*)(lds + PG8_SB(b, h) + boff + n * 2048 + k * 1024); } while (0)
; #define PG8_MMA(ai, bj, At, Bt) do { __builtin_amdgcn_s_setprio(1); _Pragma("unroll") for (int m = 0; m < 4; ++m) _Pragma("unroll") for (int n = 0; n < 2; ++n) _Pragma("unroll") for (int k = 0; k < 2; ++k) \
;         acc[ai][bj][m][n] = __builtin_amdgcn_mfma_f32_16x16x32_bf16(Bt[n][k], At[m][k], acc[ai][bj][m][n], 0, 0, 0); __builtin_amdgcn_s_setprio(0); } while (0)
; #define PG8_WAIT_V(n) asm volatile("s_waitcnt vmcnt(" #n ")" ::: "memory")
; #define PG8_WAIT_L(n) asm volatile("s_waitcnt lgkmcnt(" #n ")" ::: "memory")
; #define PG8_BAR __builtin_amdgcn_s_barrier()
; #define PG8_SCHED __builtin_amdgcn_sched_barrier(0)
; template <class Epi, class Sched>
; __device__ __forceinline__ void gemm_phase(PG8_LAS unsigned char* lds, const Gemm g, const Sched& S, const Epi& E) {
;     ...
;             PG8_STAGE(PG8_SB(0, 1), b2 + hstep, voffB);
;             PG8_WAIT_V(6); PG8_BAR; PG8_MMA(1, 1, At, B1); PG8_BAR;
;             PG8_LDB(B0, 1, 0); PG8_SCHED; PG8_LDA(At, 1, 0); PG8_STAGE(PG8_SA(0, 1), a2 + hstep, voffA);
;             PG8_WAIT_L(8); PG8_BAR; PG8_WAIT_L(0); PG8_MMA(0, 0, At, B0); PG8_BAR; PG8_SCHED;
;             PG8_LDB(B1, 1, 1); PG8_STAGE(PG8_SB(1, 0), b3, voffB);
;             PG8_BAR; PG8_WAIT_L(0); PG8_MMA(0, 1, At, B1); PG8_BAR;
;             PG8_LDA(At, 1, 1); PG8_STAGE(PG8_SA(1, 0), a3, voffA);
;             PG8_BAR; PG8_WAIT_L(0); PG8_MMA(1, 0, At, B0); PG8_BAR; PG8_SCHED;
;             PG8_STAGE(PG8_SB(1, 1), b3 + hstep, voffB);
;             PG8_WAIT_V(6); PG8_BAR; PG8_MMA(1, 1, At, B1); PG8_BAR;
	s_add_u32 s56, s20, 0x40000
	s_addc_u32 s57, s21, 0
	s_add_i32 s51, s59, s28
	v_lshl_add_u64 v[150:151], s[56:57], 0, v[0:1]
	s_mov_b32 m0, s51
	s_nop 0
	global_load_lds_dwordx4 v[150:151], off
	v_lshl_add_u64 v[150:151], s[56:57], 0, v[134:135]
	s_add_i32 m0, s51, 0x2000
	s_nop 0
	global_load_lds_dwordx4 v[150:151], off
	s_waitcnt vmcnt(6)
	s_barrier
	v_mfma_f32_16x16x32_bf16 v[54:57], v[216:219], v[184:187], v[54:57]
	v_mfma_f32_16x16x32_bf16 v[46:49], v[224:227], v[184:187], v[46:49]
	v_mfma_f32_16x16x32_bf16 v[38:41], v[216:219], v[192:195], v[38:41]
	v_mfma_f32_16x16x32_bf16 v[30:33], v[224:227], v[192:195], v[30:33]
	v_mfma_f32_16x16x32_bf16 v[22:25], v[216:219], v[200:203], v[22:25]
	v_mfma_f32_16x16x32_bf16 v[14:17], v[224:227], v[200:203], v[14:17]
	v_mfma_f32_16x16x32_bf16 v[6:9], v[216:219], v[208:211], v[6:9]
	v_mfma_f32_16x16x32_bf16 v[2:5], v[224:227], v[208:211], v[2:5]
	v_mfma_f32_16x16x32_bf16 v[54:57], v[220:223], v[188:191], v[54:57]
	v_mfma_f32_16x16x32_bf16 v[46:49], v[228:231], v[188:191], v[46:49]
	v_mfma_f32_16x16x32_bf16 v[38:41], v[220:223], v[196:199], v[38:41]
	v_mfma_f32_16x16x32_bf16 v[30:33], v[228:231], v[196:199], v[30:33]
	v_mfma_f32_16x16x32_bf16 v[22:25], v[220:223], v[204:207], v[22:25]
	v_mfma_f32_16x16x32_bf16 v[14:17], v[228:231], v[204:207], v[14:17]
	v_mfma_f32_16x16x32_bf16 v[6:9], v[220:223], v[212:215], v[6:9]
	v_mfma_f32_16x16x32_bf16 v[2:5], v[228:231], v[212:215], v[2:5]
	s_add_i32 s51, 0, 0x18000
	v_add_u32_e32 v175, s51, v147
	s_barrier
	ds_read_b128 v[150:153], v175
	ds_read_b128 v[154:157], v175 offset:1024
	ds_read_b128 v[176:179], v175 offset:2048
	ds_read_b128 v[180:183], v175 offset:3072
	s_add_u32 s22, s22, 0x40000
	s_addc_u32 s23, s23, 0
	s_mov_b32 m0, s31
	v_lshl_add_u64 v[216:217], s[22:23], 0, v[138:139]
	ds_read_b128 v[184:187], v149 offset:32768
	ds_read_b128 v[188:191], v149 offset:33792
	ds_read_b128 v[192:195], v149 offset:34816
	ds_read_b128 v[196:199], v149 offset:35840
	ds_read_b128 v[200:203], v149 offset:36864
	ds_read_b128 v[204:207], v149 offset:37888
	ds_read_b128 v[208:211], v149 offset:38912
	ds_read_b128 v[212:215], v149 offset:39936
	global_load_lds_dwordx4 v[216:217], off
	v_lshl_add_u64 v[216:217], s[22:23], 0, v[136:137]
	s_mov_b32 m0, s34
	s_nop 0
	global_load_lds_dwordx4 v[216:217], off
	s_waitcnt lgkmcnt(8)
	s_barrier
	s_waitcnt lgkmcnt(0)
	s_waitcnt lgkmcnt(0)
	v_mfma_f32_16x16x32_bf16 v[126:129], v[150:153], v[184:187], v[126:129]
	v_mfma_f32_16x16x32_bf16 v[122:125], v[176:179], v[184:187], v[122:125]
	v_mfma_f32_16x16x32_bf16 v[118:121], v[150:153], v[192:195], v[118:121]
	v_mfma_f32_16x16x32_bf16 v[110:113], v[176:179], v[192:195], v[110:113]
	v_mfma_f32_16x16x32_bf16 v[102:105], v[150:153], v[200:203], v[102:105]
	v_mfma_f32_16x16x32_bf16 v[94:97], v[176:179], v[200:203], v[94:97]
	v_mfma_f32_16x16x32_bf16 v[86:89], v[150:153], v[208:211], v[86:89]
	v_mfma_f32_16x16x32_bf16 v[78:81], v[176:179], v[208:211], v[78:81]
	v_mfma_f32_16x16x32_bf16 v[126:129], v[154:157], v[188:191], v[126:129]
	v_mfma_f32_16x16x32_bf16 v[122:125], v[180:183], v[188:191], v[122:125]
	v_mfma_f32_16x16x32_bf16 v[118:121], v[154:157], v[196:199], v[118:121]
	v_mfma_f32_16x16x32_bf16 v[110:113], v[180:183], v[196:199], v[110:113]
	v_mfma_f32_16x16x32_bf16 v[102:105], v[154:157], v[204:207], v[102:105]
	v_mfma_f32_16x16x32_bf16 v[94:97], v[180:183], v[204:207], v[94:97]
	v_mfma_f32_16x16x32_bf16 v[86:89], v[154:157], v[212:215], v[86:89]
	v_mfma_f32_16x16x32_bf16 v[78:81], v[180:183], v[212:215], v[78:81]
	s_barrier
	s_add_i32 s22, 0, 0x1c000
	s_add_i32 s23, s51, s28
	v_add_u32_e32 v175, s22, v147
	v_lshl_add_u64 v[144:145], v[144:145], 0, s[70:71]
	s_mov_b32 m0, s23
	ds_read_b128 v[216:219], v175
	ds_read_b128 v[220:223], v175 offset:1024
	ds_read_b128 v[224:227], v175 offset:2048
	ds_read_b128 v[228:231], v175 offset:3072
	global_load_lds_dwordx4 v[144:145], off
	v_lshl_add_u64 v[144:145], v[158:159], 0, s[70:71]
	s_add_i32 m0, s23, 0x2000
	s_nop 0
	global_load_lds_dwordx4 v[144:145], off
	s_barrier
; #define PG8_STAGE(bufoff, gbase, voff) do { _Pragma("unroll") for (int _i = 0; _i < 2; ++_i) \
;         __builtin_amdgcn_global_load_lds((const unsigned*)((const char*)(gbase) + (voff)[_i]), (PG8_LAS unsigned*)(lds + (bufoff) + ldsw + _i * 8192), 16, 0, 0); } while (0)
; #define PG8_LDA(dst, b, h) do { _Pragma("unroll") for (int m = 0; m < 4; ++m) _Pragma("unroll") for (int k = 0; k < 2; ++k) dst[m][k] = *(const PG8_LAS bf16x8*)(lds + PG8_SA(b, h) + aoff + m * 2048 + k * 1024); } while (0)
; #define PG8_LDB(dst, b, h) do { _Pragma("unroll") for (int n = 0; n < 2; ++n) _Pragma("unroll") for (int k = 0; k < 2; ++k) dst[n][k] = *(const PG8_LAS bf16x8*)(lds + PG8_SB(b, h) + boff + n * 2048 + k * 1024); } while (0)
; #define PG8_MMA(ai, bj, At, Bt) do { __builtin_amdgcn_s_setprio(1); _Pragma("unroll") for (int m = 0; m < 4; ++m) _Pragma("unroll") for (int n = 0; n < 2; ++n) _Pragma("unroll") for (int k = 0; k < 2; ++k) \
;         acc[ai][bj][m][n] = __builtin_amdgcn_mfma_f32_16x16x32_bf16(Bt[n][k], At[m][k], acc[ai][bj][m][n], 0, 0, 0); __builtin_amdgcn_s_setprio(0); } while (0)
; #define PG8_WAIT_V(n) asm volatile("s_waitcnt vmcnt(" #n ")" ::: "memory")
; template <class Epi, class Sched>
; __device__ __forceinline__ void gemm_phase(PG8_LAS unsigned char* lds, const Gemm g, const Sched& S, const Epi& E) {
;     ...
;             PG8_WAIT_V(6); PG8_BAR; PG8_MMA(1, 1, At, B1); PG8_BAR;
;             PG8_LDB(B0, 1, 0); PG8_SCHED; PG8_LDA(At, 1, 0); PG8_STAGE(PG8_SA(0, 1), a2 + hstep, voffA);
;             PG8_WAIT_L(8); PG8_BAR; PG8_WAIT_L(0); PG8_MMA(0, 0, At, B0); PG8_BAR; PG8_SCHED;
;             PG8_LDB(B1, 1, 1); PG8_STAGE(PG8_SB(1, 0), b3, voffB);
;             PG8_BAR; PG8_WAIT_L(0); PG8_MMA(0, 1, At, B1); PG8_BAR;
;             PG8_LDA(At, 1, 1); PG8_STAGE(PG8_SA(1, 0), a3, voffA);
;             PG8_BAR; PG8_WAIT_L(0); PG8_MMA(1, 0, At, B0); PG8_BAR; PG8_SCHED;
;             PG8_STAGE(PG8_SB(1, 1), b3 + hstep, voffB);
;             PG8_WAIT_V(6); PG8_BAR; PG8_MMA(1, 1, At, B1); PG8_BAR;
;     __device__ __forceinline__ void operator()(const f32x4 (&acc)[2][2][4][2], const pg8::Unit& u, int wr, int wc, int fr, int fq) const {
;     ...
;         if (u.pn < 6) { base = PR; pitch = PRW; colt = 256 * u.pn; }
;         else if (u.pn < 12) { base = PH; pitch = PHG; colt = 256 * (u.pn - 6); }
;         else { base = PG; pitch = PGL; colt = 256 * (u.pn - 12); }
	s_waitcnt lgkmcnt(0)
	s_waitcnt lgkmcnt(0)
	v_mfma_f32_16x16x32_bf16 v[114:117], v[216:219], v[184:187], v[114:117]
	v_mfma_f32_16x16x32_bf16 v[106:109], v[224:227], v[184:187], v[106:109]
	v_mfma_f32_16x16x32_bf16 v[98:101], v[216:219], v[192:195], v[98:101]
	v_mfma_f32_16x16x32_bf16 v[90:93], v[224:227], v[192:195], v[90:93]
	v_mfma_f32_16x16x32_bf16 v[82:85], v[216:219], v[200:203], v[82:85]
	v_mfma_f32_16x16x32_bf16 v[74:77], v[224:227], v[200:203], v[74:77]
	v_mfma_f32_16x16x32_bf16 v[70:73], v[216:219], v[208:211], v[70:73]
	v_mfma_f32_16x16x32_bf16 v[66:69], v[224:227], v[208:211], v[66:69]
	v_mfma_f32_16x16x32_bf16 v[114:117], v[220:223], v[188:191], v[114:117]
	v_mfma_f32_16x16x32_bf16 v[106:109], v[228:231], v[188:191], v[106:109]
	v_mfma_f32_16x16x32_bf16 v[98:101], v[220:223], v[196:199], v[98:101]
	v_mfma_f32_16x16x32_bf16 v[90:93], v[228:231], v[196:199], v[90:93]
	v_mfma_f32_16x16x32_bf16 v[82:85], v[220:223], v[204:207], v[82:85]
	v_mfma_f32_16x16x32_bf16 v[74:77], v[228:231], v[204:207], v[74:77]
	v_mfma_f32_16x16x32_bf16 v[70:73], v[220:223], v[212:215], v[70:73]
	v_mfma_f32_16x16x32_bf16 v[66:69], v[228:231], v[212:215], v[66:69]
	s_mov_b32 m0, s35
	v_lshl_add_u64 v[144:145], v[232:233], 0, s[70:71]
	s_barrier
	ds_read_b128 v[184:187], v149 offset:49152
	ds_read_b128 v[188:191], v149 offset:50176
	ds_read_b128 v[192:195], v149 offset:51200
	ds_read_b128 v[196:199], v149 offset:52224
	ds_read_b128 v[200:203], v149 offset:53248
	ds_read_b128 v[204:207], v149 offset:54272
	ds_read_b128 v[208:211], v149 offset:55296
	ds_read_b128 v[212:215], v149 offset:56320
	global_load_lds_dwordx4 v[144:145], off
	v_lshl_add_u64 v[144:145], v[234:235], 0, s[70:71]
	s_mov_b32 m0, s36
	s_nop 0
	global_load_lds_dwordx4 v[144:145], off
	s_barrier
	s_waitcnt lgkmcnt(0)
	s_waitcnt lgkmcnt(0)
	v_mfma_f32_16x16x32_bf16 v[62:65], v[150:153], v[184:187], v[62:65]
	v_mfma_f32_16x16x32_bf16 v[58:61], v[176:179], v[184:187], v[58:61]
	v_mfma_f32_16x16x32_bf16 v[50:53], v[150:153], v[192:195], v[50:53]
	v_mfma_f32_16x16x32_bf16 v[42:45], v[176:179], v[192:195], v[42:45]
	v_mfma_f32_16x16x32_bf16 v[34:37], v[150:153], v[200:203], v[34:37]
	v_mfma_f32_16x16x32_bf16 v[26:29], v[176:179], v[200:203], v[26:29]
	v_mfma_f32_16x16x32_bf16 v[18:21], v[150:153], v[208:211], v[18:21]
	v_mfma_f32_16x16x32_bf16 v[10:13], v[176:179], v[208:211], v[10:13]
	v_mfma_f32_16x16x32_bf16 v[62:65], v[154:157], v[188:191], v[62:65]
	v_mfma_f32_16x16x32_bf16 v[58:61], v[180:183], v[188:191], v[58:61]
	v_mfma_f32_16x16x32_bf16 v[50:53], v[154:157], v[196:199], v[50:53]
	v_mfma_f32_16x16x32_bf16 v[42:45], v[180:183], v[196:199], v[42:45]
	v_mfma_f32_16x16x32_bf16 v[34:37], v[154:157], v[204:207], v[34:37]
	v_mfma_f32_16x16x32_bf16 v[26:29], v[180:183], v[204:207], v[26:29]
	v_mfma_f32_16x16x32_bf16 v[18:21], v[154:157], v[212:215], v[18:21]
	v_mfma_f32_16x16x32_bf16 v[10:13], v[180:183], v[212:215], v[10:13]
	s_barrier
	s_add_u32 s20, s20, 0x40080
	s_addc_u32 s21, s21, 0
	s_add_i32 s22, s22, s28
	v_lshl_add_u64 v[144:145], s[20:21], 0, v[0:1]
	s_mov_b32 m0, s22
	s_nop 0
	global_load_lds_dwordx4 v[144:145], off
	v_lshl_add_u64 v[144:145], s[20:21], 0, v[134:135]
	s_add_i32 m0, s22, 0x2000
	s_nop 0
	global_load_lds_dwordx4 v[144:145], off
	s_waitcnt vmcnt(6)
	s_barrier
	v_mfma_f32_16x16x32_bf16 v[54:57], v[216:219], v[184:187], v[54:57]
	v_mfma_f32_16x16x32_bf16 v[46:49], v[224:227], v[184:187], v[46:49]
	v_mfma_f32_16x16x32_bf16 v[38:41], v[216:219], v[192:195], v[38:41]
	v_mfma_f32_16x16x32_bf16 v[30:33], v[224:227], v[192:195], v[30:33]
	v_mfma_f32_16x16x32_bf16 v[22:25], v[216:219], v[200:203], v[22:25]
	v_mfma_f32_16x16x32_bf16 v[14:17], v[224:227], v[200:203], v[14:17]
	v_mfma_f32_16x16x32_bf16 v[6:9], v[216:219], v[208:211], v[6:9]
	v_mfma_f32_16x16x32_bf16 v[2:5], v[224:227], v[208:211], v[2:5]
	v_mfma_f32_16x16x32_bf16 v[54:57], v[220:223], v[188:191], v[54:57]
	v_mfma_f32_16x16x32_bf16 v[46:49], v[228:231], v[188:191], v[46:49]
	v_mfma_f32_16x16x32_bf16 v[38:41], v[220:223], v[196:199], v[38:41]
	v_mfma_f32_16x16x32_bf16 v[30:33], v[228:231], v[196:199], v[30:33]
	v_mfma_f32_16x16x32_bf16 v[22:25], v[220:223], v[204:207], v[22:25]
	v_mfma_f32_16x16x32_bf16 v[14:17], v[228:231], v[204:207], v[14:17]
	v_mfma_f32_16x16x32_bf16 v[6:9], v[220:223], v[212:215], v[6:9]
	v_mfma_f32_16x16x32_bf16 v[2:5], v[228:231], v[212:215], v[2:5]
	s_add_i32 s50, s50, 2
	s_add_u32 s18, s18, 0x100
	s_addc_u32 s19, s19, 0
	s_add_u32 s44, s44, 0x100
	s_addc_u32 s45, s45, 0
	s_cmp_gt_u32 s50, 13
	s_barrier
	s_cbranch_scc0 .LBB0_1071
	s_cmp_gt_i32 s39, 5
	s_mov_b64 s[22:23], -1
	s_cbranch_scc0 .LBB0_1078
	s_lshl_b32 s13, s39, 8
	s_cmp_gt_u32 s39, 11
	s_mov_b64 s[20:21], -1
	s_cbranch_scc0 .LBB0_1075
	s_add_i32 s11, s13, 0xfffff400
	s_mov_b64 s[20:21], 0

; #define PG8_STAGE(bufoff, gbase, voff) do { _Pragma("unroll") for (int _i = 0; _i < 2; ++_i) \
;         __builtin_amdgcn_global_load_lds((const unsigned*)((const char*)(gbase) + (voff)[_i]), (PG8_LAS unsigned*)(lds + (bufoff) + ldsw + _i * 8192), 16, 0, 0); } while (0)
; #define PG8_LDA(dst, b, h) do { _Pragma("unroll") for (int m = 0; m < 4; ++m) _Pragma("unroll") for (int k = 0; k < 2; ++k) dst[m][k] = *(const PG8_LAS bf16x8*)(lds + PG8_SA(b, h) + aoff + m * 2048 + k * 1024); } while (0)
; #define PG8_LDB(dst, b, h) do { _Pragma("unroll") for (int n = 0; n < 2; ++n) _Pragma("unroll") for (int k = 0; k < 2; ++k) dst[n][k] = *(const PG8_LAS bf16x8*)(lds + PG8_SB(b, h) + boff + n * 2048 + k * 1024); } while (0)
; #define PG8_MMA(ai, bj, At, Bt) do { __builtin_amdgcn_s_setprio(1); _Pragma("unroll") for (int m = 0; m < 4; ++m) _Pragma("unroll") for (int n = 0; n < 2; ++n) _Pragma("unroll") for (int k = 0; k < 2; ++k) \
;         acc[ai][bj][m][n] = __builtin_amdgcn_mfma_f32_16x16x32_bf16(Bt[n][k], At[m][k], acc[ai][bj][m][n], 0, 0, 0); __builtin_amdgcn_s_setprio(0); } while (0)
; #define PG8_WAIT_V(n) asm volatile("s_waitcnt vmcnt(" #n ")" ::: "memory")
; template <class Epi, class Sched>
; __device__ __forceinline__ void gemm_phase(PG8_LAS unsigned char* lds, const Gemm g, const Sched& S, const Epi& E) {
;     ...
;         for (int t = 0; t < nt; t += 2) {
;             const bool last = (t == nt - 2);
;             const char* a1 = cA + (size_t)(t + 1) * kstep;
;             const char* a2 = last ? nA : cA + (size_t)(t + 2) * kstep; const char* b2 = last ? nB : cB + (size_t)(t + 2) * kstep;
;             const char* a3 = a2 + kstep; const char* b3 = b2 + kstep;
;             if (last && has_next) S.a_ready(nxt);
;             PG8_LDB(B0, 0, 0); PG8_SCHED; PG8_LDA(At, 0, 0); PG8_STAGE(PG8_SA(1, 1), a1 + hstep, voffA);
;             PG8_WAIT_L(8); PG8_BAR; PG8_WAIT_L(0); PG8_MMA(0, 0, At, B0); PG8_BAR; PG8_SCHED;
;             PG8_LDB(B1, 0, 1); PG8_STAGE(PG8_SB(0, 0), b2, voffB);
;             PG8_BAR; PG8_WAIT_L(0); PG8_MMA(0, 1, At, B1); PG8_BAR;
;             PG8_LDA(At, 0, 1); PG8_STAGE(PG8_SA(0, 0), a2, voffA);
;             PG8_BAR; PG8_WAIT_L(0); PG8_MMA(1, 0, At, B0); PG8_BAR; PG8_SCHED;
;             PG8_STAGE(PG8_SB(0, 1), b2 + hstep, voffB);
;             PG8_WAIT_V(6); PG8_BAR; PG8_MMA(1, 1, At, B1); PG8_BAR;
.LBB0_1106:
	s_add_i32 s41, s12, 2
	s_add_u32 s14, s10, 0x80
	s_addc_u32 s13, s11, 0
	s_add_i32 s44, 0, 0x10000
	v_add_u32_e32 v137, s44, v151
	ds_read_b128 v[144:147], v137
	ds_read_b128 v[154:157], v137 offset:1024
	ds_read_b128 v[176:179], v137 offset:2048
	ds_read_b128 v[180:183], v137 offset:3072
	s_cmp_eq_u32 s31, s12
	s_cselect_b32 s12, s0, s14
	s_cselect_b32 s13, s1, s13
	s_cselect_b32 s15, s7, s40
	s_cselect_b32 s14, s6, s39
	v_lshl_add_u64 v[148:149], s[10:11], 0, v[140:141]
	s_add_i32 m0, s22, 0xc000
	ds_read_b128 v[184:187], v153
	ds_read_b128 v[188:191], v153 offset:1024
	ds_read_b128 v[192:195], v153 offset:2048
	ds_read_b128 v[196:199], v153 offset:3072
	ds_read_b128 v[200:203], v153 offset:4096
	ds_read_b128 v[204:207], v153 offset:5120
	ds_read_b128 v[208:211], v153 offset:6144
	ds_read_b128 v[212:215], v153 offset:7168
	global_load_lds_dwordx4 v[148:149], off
	v_lshl_add_u64 v[148:149], s[10:11], 0, v[142:143]
	s_add_i32 m0, s22, 0xe000
	s_nop 0
	global_load_lds_dwordx4 v[148:149], off
	s_waitcnt lgkmcnt(8)
	s_barrier
	s_waitcnt lgkmcnt(0)
	s_waitcnt lgkmcnt(0)
	v_mfma_f32_16x16x32_bf16 v[126:129], v[144:147], v[184:187], v[126:129]
	v_mfma_f32_16x16x32_bf16 v[122:125], v[176:179], v[184:187], v[122:125]
	v_mfma_f32_16x16x32_bf16 v[110:113], v[144:147], v[192:195], v[110:113]
	v_mfma_f32_16x16x32_bf16 v[106:109], v[176:179], v[192:195], v[106:109]
	v_mfma_f32_16x16x32_bf16 v[94:97], v[144:147], v[200:203], v[94:97]
	v_mfma_f32_16x16x32_bf16 v[90:93], v[176:179], v[200:203], v[90:93]
	v_mfma_f32_16x16x32_bf16 v[78:81], v[144:147], v[208:211], v[78:81]
	v_mfma_f32_16x16x32_bf16 v[74:77], v[176:179], v[208:211], v[74:77]
	v_mfma_f32_16x16x32_bf16 v[126:129], v[154:157], v[188:191], v[126:129]
	v_mfma_f32_16x16x32_bf16 v[122:125], v[180:183], v[188:191], v[122:125]
	v_mfma_f32_16x16x32_bf16 v[110:113], v[154:157], v[196:199], v[110:113]
	v_mfma_f32_16x16x32_bf16 v[106:109], v[180:183], v[196:199], v[106:109]
	v_mfma_f32_16x16x32_bf16 v[94:97], v[154:157], v[204:207], v[94:97]
	v_mfma_f32_16x16x32_bf16 v[90:93], v[180:183], v[204:207], v[90:93]
	v_mfma_f32_16x16x32_bf16 v[78:81], v[154:157], v[212:215], v[78:81]
	v_mfma_f32_16x16x32_bf16 v[74:77], v[180:183], v[212:215], v[74:77]
	s_barrier
	s_add_i32 s45, 0, 0x14000
	s_add_i32 s44, s44, s17
	v_add_u32_e32 v137, s45, v151
	v_lshl_add_u64 v[148:149], s[14:15], 0, v[0:1]
	s_mov_b32 m0, s44
	ds_read_b128 v[216:219], v137
	ds_read_b128 v[220:223], v137 offset:1024
	ds_read_b128 v[224:227], v137 offset:2048
	ds_read_b128 v[228:231], v137 offset:3072
	global_load_lds_dwordx4 v[148:149], off
	v_lshl_add_u64 v[158:159], s[14:15], 0, v[134:135]
	s_add_i32 m0, s44, 0x2000
	s_nop 0
	global_load_lds_dwordx4 v[158:159], off
	s_barrier
	s_waitcnt lgkmcnt(0)
	s_waitcnt lgkmcnt(0)
	v_mfma_f32_16x16x32_bf16 v[118:121], v[216:219], v[184:187], v[118:121]
	v_mfma_f32_16x16x32_bf16 v[114:117], v[224:227], v[184:187], v[114:117]
	v_mfma_f32_16x16x32_bf16 v[102:105], v[216:219], v[192:195], v[102:105]
	v_mfma_f32_16x16x32_bf16 v[98:101], v[224:227], v[192:195], v[98:101]
	v_mfma_f32_16x16x32_bf16 v[86:89], v[216:219], v[200:203], v[86:89]
	v_mfma_f32_16x16x32_bf16 v[82:85], v[224:227], v[200:203], v[82:85]
	v_mfma_f32_16x16x32_bf16 v[70:73], v[216:219], v[208:211], v[70:73]
	v_mfma_f32_16x16x32_bf16 v[66:69], v[224:227], v[208:211], v[66:69]
	v_mfma_f32_16x16x32_bf16 v[118:121], v[220:223], v[188:191], v[118:121]
	v_mfma_f32_16x16x32_bf16 v[114:117], v[228:231], v[188:191], v[114:117]
	v_mfma_f32_16x16x32_bf16 v[102:105], v[220:223], v[196:199], v[102:105]
	v_mfma_f32_16x16x32_bf16 v[98:101], v[228:231], v[196:199], v[98:101]
	v_mfma_f32_16x16x32_bf16 v[86:89], v[220:223], v[204:207], v[86:89]
	v_mfma_f32_16x16x32_bf16 v[82:85], v[228:231], v[204:207], v[82:85]
	v_mfma_f32_16x16x32_bf16 v[70:73], v[220:223], v[212:215], v[70:73]
	v_mfma_f32_16x16x32_bf16 v[66:69], v[228:231], v[212:215], v[66:69]
	s_mov_b32 m0, s22
	v_lshl_add_u64 v[232:233], s[12:13], 0, v[0:1]
	s_barrier
	ds_read_b128 v[184:187], v153 offset:16384
	ds_read_b128 v[188:191], v153 offset:17408
	ds_read_b128 v[192:195], v153 offset:18432
	ds_read_b128 v[196:199], v153 offset:19456
	ds_read_b128 v[200:203], v153 offset:20480
	ds_read_b128 v[204:207], v153 offset:21504
	ds_read_b128 v[208:211], v153 offset:22528
	ds_read_b128 v[212:215], v153 offset:23552
	global_load_lds_dwordx4 v[232:233], off
	v_lshl_add_u64 v[234:235], s[12:13], 0, v[134:135]
	s_mov_b32 m0, s23
	s_nop 0
	global_load_lds_dwordx4 v[234:235], off
	s_barrier
	s_waitcnt lgkmcnt(0)
	s_waitcnt lgkmcnt(0)
	v_mfma_f32_16x16x32_bf16 v[62:65], v[144:147], v[184:187], v[62:65]
	v_mfma_f32_16x16x32_bf16 v[58:61], v[176:179], v[184:187], v[58:61]
	v_mfma_f32_16x16x32_bf16 v[46:49], v[144:147], v[192:195], v[46:49]
	v_mfma_f32_16x16x32_bf16 v[42:45], v[176:179], v[192:195], v[42:45]
	v_mfma_f32_16x16x32_bf16 v[30:33], v[144:147], v[200:203], v[30:33]
	v_mfma_f32_16x16x32_bf16 v[26:29], v[176:179], v[200:203], v[26:29]
	v_mfma_f32_16x16x32_bf16 v[14:17], v[144:147], v[208:211], v[14:17]
	v_mfma_f32_16x16x32_bf16 v[10:13], v[176:179], v[208:211], v[10:13]
	v_mfma_f32_16x16x32_bf16 v[62:65], v[154:157], v[188:191], v[62:65]
	v_mfma_f32_16x16x32_bf16 v[58:61], v[180:183], v[188:191], v[58:61]
	v_mfma_f32_16x16x32_bf16 v[46:49], v[154:157], v[196:199], v[46:49]
	v_mfma_f32_16x16x32_bf16 v[42:45], v[180:183], v[196:199], v[42:45]
	v_mfma_f32_16x16x32_bf16 v[30:33], v[154:157], v[204:207], v[30:33]
	v_mfma_f32_16x16x32_bf16 v[26:29], v[180:183], v[204:207], v[26:29]
	v_mfma_f32_16x16x32_bf16 v[14:17], v[154:157], v[212:215], v[14:17]
	v_mfma_f32_16x16x32_bf16 v[10:13], v[180:183], v[212:215], v[10:13]
	s_barrier
; #define PG8_STAGE(bufoff, gbase, voff) do { _Pragma("unroll") for (int _i = 0; _i < 2; ++_i) \
;         __builtin_amdgcn_global_load_lds((const unsigned*)((const char*)(gbase) + (voff)[_i]), (PG8_LAS unsigned*)(lds + (bufoff) + ldsw + _i * 8192), 16, 0, 0); } while (0)
; #define PG8_LDA(dst, b, h) do { _Pragma("unroll") for (int m = 0; m < 4; ++m) _Pragma("unroll") for (int k = 0; k < 2; ++k) dst[m][k] = *(const PG8_LAS bf16x8*)(lds + PG8_SA(b, h) + aoff + m * 2048 + k * 1024); } while (0)
; #define PG8_LDB(dst, b, h) do { _Pragma("unroll") for (int n = 0; n < 2; ++n) _Pragma("unroll") for (int k = 0; k < 2; ++k) dst[n][k] = *(const PG8_LAS bf16x8*)(lds + PG8_SB(b, h) + boff + n * 2048 + k * 1024); } while (0)
; #define PG8_MMA(ai, bj, At, Bt) do { __builtin_amdgcn_s_setprio(1); _Pragma("unroll") for (int m = 0; m < 4; ++m) _Pragma("unroll") for (int n = 0; n < 2; ++n) _Pragma("unroll") for (int k = 0; k < 2; ++k) \
;         acc[ai][bj][m][n] = __builtin_amdgcn_mfma_f32_16x16x32_bf16(Bt[n][k], At[m][k], acc[ai][bj][m][n], 0, 0, 0); __builtin_amdgcn_s_setprio(0); } while (0)
; #define PG8_WAIT_V(n) asm volatile("s_waitcnt vmcnt(" #n ")" ::: "memory")
; #define PG8_WAIT_L(n) asm volatile("s_waitcnt lgkmcnt(" #n ")" ::: "memory")
; #define PG8_BAR __builtin_amdgcn_s_barrier()
; #define PG8_SCHED __builtin_amdgcn_sched_barrier(0)
; template <class Epi, class Sched>
; __device__ __forceinline__ void gemm_phase(PG8_LAS unsigned char* lds, const Gemm g, const Sched& S, const Epi& E) {
;     ...
;             PG8_STAGE(PG8_SB(0, 1), b2 + hstep, voffB);
;             PG8_WAIT_V(6); PG8_BAR; PG8_MMA(1, 1, At, B1); PG8_BAR;
;             PG8_LDB(B0, 1, 0); PG8_SCHED; PG8_LDA(At, 1, 0); PG8_STAGE(PG8_SA(0, 1), a2 + hstep, voffA);
;             PG8_WAIT_L(8); PG8_BAR; PG8_WAIT_L(0); PG8_MMA(0, 0, At, B0); PG8_BAR; PG8_SCHED;
;             PG8_LDB(B1, 1, 1); PG8_STAGE(PG8_SB(1, 0), b3, voffB);
;             PG8_BAR; PG8_WAIT_L(0); PG8_MMA(0, 1, At, B1); PG8_BAR;
;             PG8_LDA(At, 1, 1); PG8_STAGE(PG8_SA(1, 0), a3, voffA);
	s_add_u32 s14, s14, s72
	s_addc_u32 s15, s15, 0
	s_add_i32 s44, s45, s17
	v_lshl_add_u64 v[236:237], s[14:15], 0, v[0:1]
	s_mov_b32 m0, s44
	v_lshl_add_u64 v[238:239], s[14:15], 0, v[134:135]
	global_load_lds_dwordx4 v[236:237], off
	s_add_i32 m0, s44, 0x2000
	s_nop 0
	global_load_lds_dwordx4 v[238:239], off
	s_waitcnt vmcnt(6)
	s_barrier
	v_mfma_f32_16x16x32_bf16 v[54:57], v[216:219], v[184:187], v[54:57]
	v_mfma_f32_16x16x32_bf16 v[50:53], v[224:227], v[184:187], v[50:53]
	v_mfma_f32_16x16x32_bf16 v[38:41], v[216:219], v[192:195], v[38:41]
	v_mfma_f32_16x16x32_bf16 v[34:37], v[224:227], v[192:195], v[34:37]
	v_mfma_f32_16x16x32_bf16 v[22:25], v[216:219], v[200:203], v[22:25]
	v_mfma_f32_16x16x32_bf16 v[18:21], v[224:227], v[200:203], v[18:21]
	v_mfma_f32_16x16x32_bf16 v[6:9], v[216:219], v[208:211], v[6:9]
	v_mfma_f32_16x16x32_bf16 v[2:5], v[224:227], v[208:211], v[2:5]
	v_mfma_f32_16x16x32_bf16 v[54:57], v[220:223], v[188:191], v[54:57]
	v_mfma_f32_16x16x32_bf16 v[50:53], v[228:231], v[188:191], v[50:53]
	v_mfma_f32_16x16x32_bf16 v[38:41], v[220:223], v[196:199], v[38:41]
	v_mfma_f32_16x16x32_bf16 v[34:37], v[228:231], v[196:199], v[34:37]
	v_mfma_f32_16x16x32_bf16 v[22:25], v[220:223], v[204:207], v[22:25]
	v_mfma_f32_16x16x32_bf16 v[18:21], v[228:231], v[204:207], v[18:21]
	v_mfma_f32_16x16x32_bf16 v[6:9], v[220:223], v[212:215], v[6:9]
	v_mfma_f32_16x16x32_bf16 v[2:5], v[228:231], v[212:215], v[2:5]
	s_add_i32 s14, 0, 0x18000
	v_add_u32_e32 v137, s14, v151
	s_barrier
	ds_read_b128 v[144:147], v137
	ds_read_b128 v[154:157], v137 offset:1024
	ds_read_b128 v[176:179], v137 offset:2048
	ds_read_b128 v[180:183], v137 offset:3072
	s_add_u32 s12, s12, s72
	s_addc_u32 s13, s13, 0
	s_mov_b32 m0, s26
	v_lshl_add_u64 v[216:217], s[12:13], 0, v[0:1]
	ds_read_b128 v[184:187], v153 offset:32768
	ds_read_b128 v[188:191], v153 offset:33792
	ds_read_b128 v[192:195], v153 offset:34816
	ds_read_b128 v[196:199], v153 offset:35840
	ds_read_b128 v[200:203], v153 offset:36864
	ds_read_b128 v[204:207], v153 offset:37888
	ds_read_b128 v[208:211], v153 offset:38912
	ds_read_b128 v[212:215], v153 offset:39936
	global_load_lds_dwordx4 v[216:217], off
	v_lshl_add_u64 v[216:217], s[12:13], 0, v[134:135]
	s_mov_b32 m0, s27
	s_nop 0
	global_load_lds_dwordx4 v[216:217], off
	s_waitcnt lgkmcnt(8)
	s_barrier
	s_waitcnt lgkmcnt(0)
	s_waitcnt lgkmcnt(0)
	v_mfma_f32_16x16x32_bf16 v[126:129], v[144:147], v[184:187], v[126:129]
	v_mfma_f32_16x16x32_bf16 v[122:125], v[176:179], v[184:187], v[122:125]
	v_mfma_f32_16x16x32_bf16 v[110:113], v[144:147], v[192:195], v[110:113]
	v_mfma_f32_16x16x32_bf16 v[106:109], v[176:179], v[192:195], v[106:109]
	v_mfma_f32_16x16x32_bf16 v[94:97], v[144:147], v[200:203], v[94:97]
	v_mfma_f32_16x16x32_bf16 v[90:93], v[176:179], v[200:203], v[90:93]
	v_mfma_f32_16x16x32_bf16 v[78:81], v[144:147], v[208:211], v[78:81]
	v_mfma_f32_16x16x32_bf16 v[74:77], v[176:179], v[208:211], v[74:77]
	v_mfma_f32_16x16x32_bf16 v[126:129], v[154:157], v[188:191], v[126:129]
	v_mfma_f32_16x16x32_bf16 v[122:125], v[180:183], v[188:191], v[122:125]
	v_mfma_f32_16x16x32_bf16 v[110:113], v[154:157], v[196:199], v[110:113]
	v_mfma_f32_16x16x32_bf16 v[106:109], v[180:183], v[196:199], v[106:109]
	v_mfma_f32_16x16x32_bf16 v[94:97], v[154:157], v[204:207], v[94:97]
	v_mfma_f32_16x16x32_bf16 v[90:93], v[180:183], v[204:207], v[90:93]
	v_mfma_f32_16x16x32_bf16 v[78:81], v[154:157], v[212:215], v[78:81]
	v_mfma_f32_16x16x32_bf16 v[74:77], v[180:183], v[212:215], v[74:77]
	s_barrier
	s_add_i32 s12, 0, 0x1c000
	s_add_i32 s13, s14, s17
	v_add_u32_e32 v137, s12, v151
	v_lshl_add_u64 v[148:149], v[148:149], 0, s[70:71]
	s_mov_b32 m0, s13
	ds_read_b128 v[216:219], v137
	ds_read_b128 v[220:223], v137 offset:1024
	ds_read_b128 v[224:227], v137 offset:2048
	ds_read_b128 v[228:231], v137 offset:3072
	global_load_lds_dwordx4 v[148:149], off
	v_lshl_add_u64 v[148:149], v[158:159], 0, s[70:71]
	s_add_i32 m0, s13, 0x2000
	s_nop 0
	global_load_lds_dwordx4 v[148:149], off
	s_barrier
	s_waitcnt lgkmcnt(0)
	s_waitcnt lgkmcnt(0)
	v_mfma_f32_16x16x32_bf16 v[118:121], v[216:219], v[184:187], v[118:121]
	v_mfma_f32_16x16x32_bf16 v[114:117], v[224:227], v[184:187], v[114:117]
	v_mfma_f32_16x16x32_bf16 v[102:105], v[216:219], v[192:195], v[102:105]
	v_mfma_f32_16x16x32_bf16 v[98:101], v[224:227], v[192:195], v[98:101]
	v_mfma_f32_16x16x32_bf16 v[86:89], v[216:219], v[200:203], v[86:89]
	v_mfma_f32_16x16x32_bf16 v[82:85], v[224:227], v[200:203], v[82:85]
	v_mfma_f32_16x16x32_bf16 v[70:73], v[216:219], v[208:211], v[70:73]
	v_mfma_f32_16x16x32_bf16 v[66:69], v[224:227], v[208:211], v[66:69]
	v_mfma_f32_16x16x32_bf16 v[118:121], v[220:223], v[188:191], v[118:121]
	v_mfma_f32_16x16x32_bf16 v[114:117], v[228:231], v[188:191], v[114:117]
	v_mfma_f32_16x16x32_bf16 v[102:105], v[220:223], v[196:199], v[102:105]
	v_mfma_f32_16x16x32_bf16 v[98:101], v[228:231], v[196:199], v[98:101]
	v_mfma_f32_16x16x32_bf16 v[86:89], v[220:223], v[204:207], v[86:89]
	v_mfma_f32_16x16x32_bf16 v[82:85], v[228:231], v[204:207], v[82:85]
	v_mfma_f32_16x16x32_bf16 v[70:73], v[220:223], v[212:215], v[70:73]
	v_mfma_f32_16x16x32_bf16 v[66:69], v[228:231], v[212:215], v[66:69]
	s_mov_b32 m0, s28
	v_lshl_add_u64 v[148:149], v[232:233], 0, s[70:71]
	s_barrier
	ds_read_b128 v[184:187], v153 offset:49152
	ds_read_b128 v[188:191], v153 offset:50176
	ds_read_b128 v[192:195], v153 offset:51200
	ds_read_b128 v[196:199], v153 offset:52224
	ds_read_b128 v[200:203], v153 offset:53248
	ds_read_b128 v[204:207], v153 offset:54272
	ds_read_b128 v[208:211], v153 offset:55296
	ds_read_b128 v[212:215], v153 offset:56320
	global_load_lds_dwordx4 v[148:149], off
	v_lshl_add_u64 v[148:149], v[234:235], 0, s[70:71]
	s_mov_b32 m0, s29
	s_nop 0
	global_load_lds_dwordx4 v[148:149], off
	s_barrier
; #define PG8_STAGE(bufoff, gbase, voff) do { _Pragma("unroll") for (int _i = 0; _i < 2; ++_i) \
;         __builtin_amdgcn_global_load_lds((const unsigned*)((const char*)(gbase) + (voff)[_i]), (PG8_LAS unsigned*)(lds + (bufoff) + ldsw + _i * 8192), 16, 0, 0); } while (0)
; #define PG8_LDA(dst, b, h) do { _Pragma("unroll") for (int m = 0; m < 4; ++m) _Pragma("unroll") for (int k = 0; k < 2; ++k) dst[m][k] = *(const PG8_LAS bf16x8*)(lds + PG8_SA(b, h) + aoff + m * 2048 + k * 1024); } while (0)
; #define PG8_MMA(ai, bj, At, Bt) do { __builtin_amdgcn_s_setprio(1); _Pragma("unroll") for (int m = 0; m < 4; ++m) _Pragma("unroll") for (int n = 0; n < 2; ++n) _Pragma("unroll") for (int k = 0; k < 2; ++k) \
;         acc[ai][bj][m][n] = __builtin_amdgcn_mfma_f32_16x16x32_bf16(Bt[n][k], At[m][k], acc[ai][bj][m][n], 0, 0, 0); __builtin_amdgcn_s_setprio(0); } while (0)
; #define PG8_WAIT_V(n) asm volatile("s_waitcnt vmcnt(" #n ")" ::: "memory")
; #define PG8_WAIT_L(n) asm volatile("s_waitcnt lgkmcnt(" #n ")" ::: "memory")
; #define PG8_BAR __builtin_amdgcn_s_barrier()
; #define PG8_SCHED __builtin_amdgcn_sched_barrier(0)
; template <class Epi, class Sched>
; __device__ __forceinline__ void gemm_phase(PG8_LAS unsigned char* lds, const Gemm g, const Sched& S, const Epi& E) {
;     ...
;             PG8_LDA(At, 1, 1); PG8_STAGE(PG8_SA(1, 0), a3, voffA);
;             PG8_BAR; PG8_WAIT_L(0); PG8_MMA(1, 0, At, B0); PG8_BAR; PG8_SCHED;
;             PG8_STAGE(PG8_SB(1, 1), b3 + hstep, voffB);
;             PG8_WAIT_V(6); PG8_BAR; PG8_MMA(1, 1, At, B1); PG8_BAR;
;     __device__ __forceinline__ void operator()(const f32x4 (&acc)[2][2][4][2], const pg8::Unit& u, int wr, int wc, int fr, int fq) const {
;         const int row0 = u.pm * 256 + wr * 64 + fr, col0 = u.pn * 256 + wc * 32 + 4 * fq;
; #pragma unroll
;         for (int ai = 0; ai < 2; ++ai)
; #pragma unroll
;             for (int m = 0; m < 4; ++m) {
;                 const size_t ro = (size_t)(row0 + ai * 128 + m * 16) * D + col0;
; #pragma unroll
;                 for (int bj = 0; bj < 2; ++bj)
; #pragma unroll
;                     for (int n = 0; n < 2; ++n) { const size_t o = ro + bj * 128 + n * 16; *(f32x4*)(X + o) = *(const f32x4*)(Xs + o) + acc[ai][bj][m][n] * scale; }
;             }
	s_waitcnt lgkmcnt(0)
	s_waitcnt lgkmcnt(0)
	v_mfma_f32_16x16x32_bf16 v[62:65], v[144:147], v[184:187], v[62:65]
	v_mfma_f32_16x16x32_bf16 v[58:61], v[176:179], v[184:187], v[58:61]
	v_mfma_f32_16x16x32_bf16 v[46:49], v[144:147], v[192:195], v[46:49]
	v_mfma_f32_16x16x32_bf16 v[42:45], v[176:179], v[192:195], v[42:45]
	v_mfma_f32_16x16x32_bf16 v[30:33], v[144:147], v[200:203], v[30:33]
	v_mfma_f32_16x16x32_bf16 v[26:29], v[176:179], v[200:203], v[26:29]
	v_mfma_f32_16x16x32_bf16 v[14:17], v[144:147], v[208:211], v[14:17]
	v_mfma_f32_16x16x32_bf16 v[10:13], v[176:179], v[208:211], v[10:13]
	v_mfma_f32_16x16x32_bf16 v[62:65], v[154:157], v[188:191], v[62:65]
	v_mfma_f32_16x16x32_bf16 v[58:61], v[180:183], v[188:191], v[58:61]
	v_mfma_f32_16x16x32_bf16 v[46:49], v[154:157], v[196:199], v[46:49]
	v_mfma_f32_16x16x32_bf16 v[42:45], v[180:183], v[196:199], v[42:45]
	v_mfma_f32_16x16x32_bf16 v[30:33], v[154:157], v[204:207], v[30:33]
	v_mfma_f32_16x16x32_bf16 v[26:29], v[180:183], v[204:207], v[26:29]
	v_mfma_f32_16x16x32_bf16 v[14:17], v[154:157], v[212:215], v[14:17]
	v_mfma_f32_16x16x32_bf16 v[10:13], v[180:183], v[212:215], v[10:13]
	s_barrier
	s_add_i32 s12, s12, s17
	v_lshl_add_u64 v[144:145], v[236:237], 0, s[70:71]
	s_mov_b32 m0, s12
	s_nop 0
	global_load_lds_dwordx4 v[144:145], off
	v_lshl_add_u64 v[144:145], v[238:239], 0, s[70:71]
	s_add_i32 m0, s12, 0x2000
	s_nop 0
	global_load_lds_dwordx4 v[144:145], off
	s_waitcnt vmcnt(6)
	s_barrier
	v_mfma_f32_16x16x32_bf16 v[54:57], v[216:219], v[184:187], v[54:57]
	v_mfma_f32_16x16x32_bf16 v[50:53], v[224:227], v[184:187], v[50:53]
	v_mfma_f32_16x16x32_bf16 v[38:41], v[216:219], v[192:195], v[38:41]
	v_mfma_f32_16x16x32_bf16 v[34:37], v[224:227], v[192:195], v[34:37]
	v_mfma_f32_16x16x32_bf16 v[22:25], v[216:219], v[200:203], v[22:25]
	v_mfma_f32_16x16x32_bf16 v[18:21], v[224:227], v[200:203], v[18:21]
	v_mfma_f32_16x16x32_bf16 v[6:9], v[216:219], v[208:211], v[6:9]
	v_mfma_f32_16x16x32_bf16 v[2:5], v[224:227], v[208:211], v[2:5]
	v_mfma_f32_16x16x32_bf16 v[54:57], v[220:223], v[188:191], v[54:57]
	v_mfma_f32_16x16x32_bf16 v[50:53], v[228:231], v[188:191], v[50:53]
	v_mfma_f32_16x16x32_bf16 v[38:41], v[220:223], v[196:199], v[38:41]
	v_mfma_f32_16x16x32_bf16 v[34:37], v[228:231], v[196:199], v[34:37]
	v_mfma_f32_16x16x32_bf16 v[22:25], v[220:223], v[204:207], v[22:25]
	v_mfma_f32_16x16x32_bf16 v[18:21], v[228:231], v[204:207], v[18:21]
	v_mfma_f32_16x16x32_bf16 v[6:9], v[220:223], v[212:215], v[6:9]
	v_mfma_f32_16x16x32_bf16 v[2:5], v[228:231], v[212:215], v[2:5]
	s_add_u32 s10, s10, 0x100
	s_addc_u32 s11, s11, 0
	s_add_u32 s39, s39, 0x100
	s_addc_u32 s40, s40, 0
	s_cmp_ge_u32 s41, s30
	s_mov_b32 s12, s41
	s_barrier
	s_cbranch_scc0 .LBB0_1106
	v_lshl_add_u32 v148, s38, 8, v150
	v_lshl_or_b32 v146, s37, 8, v152
	v_lshl_add_u32 v208, v148, 10, v146
	v_mov_b32_e32 v137, v136
	s_and_b64 vcc, exec, s[4:5]
	s_mov_b32 s37, s35
	s_mov_b32 s38, s36
	s_mov_b64 s[12:13], s[6:7]
	s_mov_b64 s[10:11], s[0:1]
	v_lshlrev_b32_e32 v208, 2, v208
	v_add_u32_e32 v209, 0x10000, v208
	v_add_u32_e32 v210, 0x20000, v208
	v_add_u32_e32 v211, 0x30000, v208
	v_add_u32_e32 v212, 0x80000, v208
	v_add_u32_e32 v213, 0x90000, v208
	v_add_u32_e32 v214, 0xa0000, v208
	v_add_u32_e32 v215, 0xb0000, v208
	global_load_dwordx4 v[176:179], v208, s[8:9]
	global_load_dwordx4 v[180:183], v208, s[8:9] offset:64
	global_load_dwordx4 v[184:187], v208, s[8:9] offset:512
	global_load_dwordx4 v[188:191], v208, s[8:9] offset:576
	global_load_dwordx4 v[192:195], v209, s[8:9]
	global_load_dwordx4 v[196:199], v209, s[8:9] offset:64
	global_load_dwordx4 v[200:203], v209, s[8:9] offset:512
	global_load_dwordx4 v[204:207], v209, s[8:9] offset:576
	s_waitcnt vmcnt(7)
	v_pk_fma_f32 v[128:129], v[136:137], v[128:129], v[178:179]
	v_pk_fma_f32 v[126:127], v[138:139], v[126:127], v[176:177]
	global_store_dwordx4 v208, v[126:129], s[92:93]
	s_waitcnt vmcnt(7)
	v_pk_fma_f32 v[124:125], v[136:137], v[124:125], v[182:183]
	v_pk_fma_f32 v[122:123], v[138:139], v[122:123], v[180:181]
	global_store_dwordx4 v208, v[122:125], s[92:93] offset:64
	s_waitcnt vmcnt(7)
	v_pk_fma_f32 v[120:121], v[136:137], v[120:121], v[186:187]
	v_pk_fma_f32 v[118:119], v[138:139], v[118:119], v[184:185]
	global_store_dwordx4 v208, v[118:121], s[92:93] offset:512
	s_waitcnt vmcnt(7)
	v_pk_fma_f32 v[116:117], v[136:137], v[116:117], v[190:191]
	v_pk_fma_f32 v[114:115], v[138:139], v[114:115], v[188:189]
	global_store_dwordx4 v208, v[114:117], s[92:93] offset:576
	global_load_dwordx4 v[176:179], v210, s[8:9]
	global_load_dwordx4 v[180:183], v210, s[8:9] offset:64
	global_load_dwordx4 v[184:187], v210, s[8:9] offset:512
	global_load_dwordx4 v[188:191], v210, s[8:9] offset:576
	s_waitcnt vmcnt(11)
	v_pk_fma_f32 v[112:113], v[136:137], v[112:113], v[194:195]
	v_pk_fma_f32 v[110:111], v[138:139], v[110:111], v[192:193]
	global_store_dwordx4 v209, v[110:113], s[92:93]
	s_waitcnt vmcnt(11)
	v_pk_fma_f32 v[108:109], v[136:137], v[108:109], v[198:199]
	v_pk_fma_f32 v[106:107], v[138:139], v[106:107], v[196:197]
	global_store_dwordx4 v209, v[106:109], s[92:93] offset:64
	s_waitcnt vmcnt(11)
	v_pk_fma_f32 v[104:105], v[136:137], v[104:105], v[202:203]
	v_pk_fma_f32 v[102:103], v[138:139], v[102:103], v[200:201]
	global_store_dwordx4 v209, v[102:105], s[92:93] offset:512
	s_waitcnt vmcnt(11)
	v_pk_fma_f32 v[100:101], v[136:137], v[100:101], v[206:207]
	v_pk_fma_f32 v[98:99], v[138:139], v[98:99], v[204:205]
	global_store_dwordx4 v209, v[98:101], s[92:93] offset:576
	global_load_dwordx4 v[192:195], v211, s[8:9]
	global_load_dwordx4 v[196:199], v211, s[8:9] offset:64
	global_load_dwordx4 v[200:203], v211, s[8:9] offset:512
	global_load_dwordx4 v[204:207], v211, s[8:9] offset:576
	s_waitcnt vmcnt(11)
;     __device__ __forceinline__ void operator()(const f32x4 (&acc)[2][2][4][2], const pg8::Unit& u, int wr, int wc, int fr, int fq) const {
;         const int row0 = u.pm * 256 + wr * 64 + fr, col0 = u.pn * 256 + wc * 32 + 4 * fq;
; #pragma unroll
;         for (int ai = 0; ai < 2; ++ai)
; #pragma unroll
;             for (int m = 0; m < 4; ++m) {
;                 const size_t ro = (size_t)(row0 + ai * 128 + m * 16) * D + col0;
; #pragma unroll
;                 for (int bj = 0; bj < 2; ++bj)
; #pragma unroll
;                     for (int n = 0; n < 2; ++n) { const size_t o = ro + bj * 128 + n * 16; *(f32x4*)(X + o) = *(const f32x4*)(Xs + o) + acc[ai][bj][m][n] * scale; }
;             }
	v_pk_fma_f32 v[96:97], v[136:137], v[96:97], v[178:179]
	v_pk_fma_f32 v[94:95], v[138:139], v[94:95], v[176:177]
	global_store_dwordx4 v210, v[94:97], s[92:93]
	s_waitcnt vmcnt(11)
	v_pk_fma_f32 v[92:93], v[136:137], v[92:93], v[182:183]
	v_pk_fma_f32 v[90:91], v[138:139], v[90:91], v[180:181]
	global_store_dwordx4 v210, v[90:93], s[92:93] offset:64
	s_waitcnt vmcnt(11)
	v_pk_fma_f32 v[88:89], v[136:137], v[88:89], v[186:187]
	v_pk_fma_f32 v[86:87], v[138:139], v[86:87], v[184:185]
	global_store_dwordx4 v210, v[86:89], s[92:93] offset:512
	s_waitcnt vmcnt(11)
	v_pk_fma_f32 v[84:85], v[136:137], v[84:85], v[190:191]
	v_pk_fma_f32 v[82:83], v[138:139], v[82:83], v[188:189]
	global_store_dwordx4 v210, v[82:85], s[92:93] offset:576
	global_load_dwordx4 v[176:179], v212, s[8:9]
	global_load_dwordx4 v[180:183], v212, s[8:9] offset:64
	global_load_dwordx4 v[184:187], v212, s[8:9] offset:512
	global_load_dwordx4 v[188:191], v212, s[8:9] offset:576
	s_waitcnt vmcnt(11)
	v_pk_fma_f32 v[80:81], v[136:137], v[80:81], v[194:195]
	v_pk_fma_f32 v[78:79], v[138:139], v[78:79], v[192:193]
	global_store_dwordx4 v211, v[78:81], s[92:93]
	s_waitcnt vmcnt(11)
	v_pk_fma_f32 v[76:77], v[136:137], v[76:77], v[198:199]
	v_pk_fma_f32 v[74:75], v[138:139], v[74:75], v[196:197]
	global_store_dwordx4 v211, v[74:77], s[92:93] offset:64
	s_waitcnt vmcnt(11)
	v_pk_fma_f32 v[72:73], v[136:137], v[72:73], v[202:203]
	v_pk_fma_f32 v[70:71], v[138:139], v[70:71], v[200:201]
	global_store_dwordx4 v211, v[70:73], s[92:93] offset:512
	s_waitcnt vmcnt(11)
	v_pk_fma_f32 v[68:69], v[136:137], v[68:69], v[206:207]
	v_pk_fma_f32 v[66:67], v[138:139], v[66:67], v[204:205]
	global_store_dwordx4 v211, v[66:69], s[92:93] offset:576
	global_load_dwordx4 v[192:195], v213, s[8:9]
	global_load_dwordx4 v[196:199], v213, s[8:9] offset:64
	global_load_dwordx4 v[200:203], v213, s[8:9] offset:512
	global_load_dwordx4 v[204:207], v213, s[8:9] offset:576
	s_waitcnt vmcnt(11)
	v_pk_fma_f32 v[64:65], v[136:137], v[64:65], v[178:179]
	v_pk_fma_f32 v[62:63], v[138:139], v[62:63], v[176:177]
	global_store_dwordx4 v212, v[62:65], s[92:93]
	s_waitcnt vmcnt(11)
	v_pk_fma_f32 v[60:61], v[136:137], v[60:61], v[182:183]
	v_pk_fma_f32 v[58:59], v[138:139], v[58:59], v[180:181]
	global_store_dwordx4 v212, v[58:61], s[92:93] offset:64
	s_waitcnt vmcnt(11)
	v_pk_fma_f32 v[56:57], v[136:137], v[56:57], v[186:187]
	v_pk_fma_f32 v[54:55], v[138:139], v[54:55], v[184:185]
	global_store_dwordx4 v212, v[54:57], s[92:93] offset:512
	s_waitcnt vmcnt(11)
	v_pk_fma_f32 v[52:53], v[136:137], v[52:53], v[190:191]
	v_pk_fma_f32 v[50:51], v[138:139], v[50:51], v[188:189]
	global_store_dwordx4 v212, v[50:53], s[92:93] offset:576
	global_load_dwordx4 v[176:179], v214, s[8:9]
	global_load_dwordx4 v[180:183], v214, s[8:9] offset:64
	global_load_dwordx4 v[184:187], v214, s[8:9] offset:512
	global_load_dwordx4 v[188:191], v214, s[8:9] offset:576
	s_waitcnt vmcnt(11)
	v_pk_fma_f32 v[48:49], v[136:137], v[48:49], v[194:195]
	v_pk_fma_f32 v[46:47], v[138:139], v[46:47], v[192:193]
	global_store_dwordx4 v213, v[46:49], s[92:93]
	s_waitcnt vmcnt(11)
	v_pk_fma_f32 v[44:45], v[136:137], v[44:45], v[198:199]
	v_pk_fma_f32 v[42:43], v[138:139], v[42:43], v[196:197]
	global_store_dwordx4 v213, v[42:45], s[92:93] offset:64
	s_waitcnt vmcnt(11)
	v_pk_fma_f32 v[40:41], v[136:137], v[40:41], v[202:203]
	v_pk_fma_f32 v[38:39], v[138:139], v[38:39], v[200:201]
	global_store_dwordx4 v213, v[38:41], s[92:93] offset:512
	s_waitcnt vmcnt(11)
	v_pk_fma_f32 v[36:37], v[136:137], v[36:37], v[206:207]
	v_pk_fma_f32 v[34:35], v[138:139], v[34:35], v[204:205]
	global_store_dwordx4 v213, v[34:37], s[92:93] offset:576
	global_load_dwordx4 v[192:195], v215, s[8:9]
	global_load_dwordx4 v[196:199], v215, s[8:9] offset:64
	global_load_dwordx4 v[200:203], v215, s[8:9] offset:512
	global_load_dwordx4 v[204:207], v215, s[8:9] offset:576
	s_waitcnt vmcnt(11)
	v_pk_fma_f32 v[32:33], v[136:137], v[32:33], v[178:179]
	v_pk_fma_f32 v[30:31], v[138:139], v[30:31], v[176:177]
	global_store_dwordx4 v214, v[30:33], s[92:93]
	s_waitcnt vmcnt(11)
	v_pk_fma_f32 v[28:29], v[136:137], v[28:29], v[182:183]
	v_pk_fma_f32 v[26:27], v[138:139], v[26:27], v[180:181]
	global_store_dwordx4 v214, v[26:29], s[92:93] offset:64
	s_waitcnt vmcnt(11)
	v_pk_fma_f32 v[24:25], v[136:137], v[24:25], v[186:187]
	v_pk_fma_f32 v[22:23], v[138:139], v[22:23], v[184:185]
	global_store_dwordx4 v214, v[22:25], s[92:93] offset:512
	s_waitcnt vmcnt(11)
	v_pk_fma_f32 v[20:21], v[136:137], v[20:21], v[190:191]
	v_pk_fma_f32 v[18:19], v[138:139], v[18:19], v[188:189]
	global_store_dwordx4 v214, v[18:21], s[92:93] offset:576
	s_waitcnt vmcnt(7)
	v_pk_fma_f32 v[16:17], v[136:137], v[16:17], v[194:195]
	v_pk_fma_f32 v[14:15], v[138:139], v[14:15], v[192:193]
	global_store_dwordx4 v215, v[14:17], s[92:93]
	s_waitcnt vmcnt(7)
	v_pk_fma_f32 v[12:13], v[136:137], v[12:13], v[198:199]
	v_pk_fma_f32 v[10:11], v[138:139], v[10:11], v[196:197]
	global_store_dwordx4 v215, v[10:13], s[92:93] offset:64
	s_waitcnt vmcnt(7)
	v_pk_fma_f32 v[8:9], v[136:137], v[8:9], v[202:203]
	v_pk_fma_f32 v[6:7], v[138:139], v[6:7], v[200:201]
	global_store_dwordx4 v215, v[6:9], s[92:93] offset:512
	s_waitcnt vmcnt(7)
	v_pk_fma_f32 v[4:5], v[136:137], v[4:5], v[206:207]
	v_pk_fma_f32 v[2:3], v[138:139], v[2:3], v[204:205]
	global_store_dwordx4 v215, v[2:5], s[92:93] offset:576
	s_cbranch_vccz .LBB0_1095
	s_waitcnt vmcnt(0)
	s_cmpk_gt_u32 s2, 0xff
	s_cbranch_scc1 .LBB0_1110
	s_barrier

; #define PG8_STAGE(bufoff, gbase, voff) do { _Pragma("unroll") for (int _i = 0; _i < 2; ++_i) \
;         __builtin_amdgcn_global_load_lds((const unsigned*)((const char*)(gbase) + (voff)[_i]), (PG8_LAS unsigned*)(lds + (bufoff) + ldsw + _i * 8192), 16, 0, 0); } while (0)
; #define PG8_LDA(dst, b, h) do { _Pragma("unroll") for (int m = 0; m < 4; ++m) _Pragma("unroll") for (int k = 0; k < 2; ++k) dst[m][k] = *(const PG8_LAS bf16x8*)(lds + PG8_SA(b, h) + aoff + m * 2048 + k * 1024); } while (0)
; #define PG8_LDB(dst, b, h) do { _Pragma("unroll") for (int n = 0; n < 2; ++n) _Pragma("unroll") for (int k = 0; k < 2; ++k) dst[n][k] = *(const PG8_LAS bf16x8*)(lds + PG8_SB(b, h) + boff + n * 2048 + k * 1024); } while (0)
; #define PG8_MMA(ai, bj, At, Bt) do { __builtin_amdgcn_s_setprio(1); _Pragma("unroll") for (int m = 0; m < 4; ++m) _Pragma("unroll") for (int n = 0; n < 2; ++n) _Pragma("unroll") for (int k = 0; k < 2; ++k) \
;         acc[ai][bj][m][n] = __builtin_amdgcn_mfma_f32_16x16x32_bf16(Bt[n][k], At[m][k], acc[ai][bj][m][n], 0, 0, 0); __builtin_amdgcn_s_setprio(0); } while (0)
; #define PG8_WAIT_V(n) asm volatile("s_waitcnt vmcnt(" #n ")" ::: "memory")
; template <class Epi, class Sched>
; __device__ __forceinline__ void gemm_phase(PG8_LAS unsigned char* lds, const Gemm g, const Sched& S, const Epi& E) {
;     ...
;         for (int t = 0; t < nt; t += 2) {
;             const bool last = (t == nt - 2);
;             const char* a1 = cA + (size_t)(t + 1) * kstep;
;             const char* a2 = last ? nA : cA + (size_t)(t + 2) * kstep; const char* b2 = last ? nB : cB + (size_t)(t + 2) * kstep;
;             const char* a3 = a2 + kstep; const char* b3 = b2 + kstep;
;             if (last && has_next) S.a_ready(nxt);
;             PG8_LDB(B0, 0, 0); PG8_SCHED; PG8_LDA(At, 0, 0); PG8_STAGE(PG8_SA(1, 1), a1 + hstep, voffA);
;             PG8_WAIT_L(8); PG8_BAR; PG8_WAIT_L(0); PG8_MMA(0, 0, At, B0); PG8_BAR; PG8_SCHED;
;             PG8_LDB(B1, 0, 1); PG8_STAGE(PG8_SB(0, 0), b2, voffB);
;             PG8_BAR; PG8_WAIT_L(0); PG8_MMA(0, 1, At, B1); PG8_BAR;
;             PG8_LDA(At, 0, 1); PG8_STAGE(PG8_SA(0, 0), a2, voffA);
;             PG8_BAR; PG8_WAIT_L(0); PG8_MMA(1, 0, At, B0); PG8_BAR; PG8_SCHED;
;             PG8_STAGE(PG8_SB(0, 1), b2 + hstep, voffB);
;             PG8_WAIT_V(6); PG8_BAR; PG8_MMA(1, 1, At, B1); PG8_BAR;
.LBB0_1129:
	s_add_u32 s16, s14, 0xfffc0080
	s_addc_u32 s17, s15, -1
	s_add_i32 s41, 0, 0x10000
	v_add_u32_e32 v175, s41, v149
	ds_read_b128 v[144:147], v175
	ds_read_b128 v[152:155], v175 offset:1024
	ds_read_b128 v[156:159], v175 offset:2048
	ds_read_b128 v[176:179], v175 offset:3072
	s_cmp_eq_u32 s40, 12
	s_cselect_b32 s19, s9, s17
	s_cselect_b32 s18, s36, s16
	s_cselect_b32 s17, s7, s39
	s_cselect_b32 s16, s37, s38
	v_lshl_add_u64 v[212:213], s[14:15], 0, v[140:141]
	s_add_i32 m0, s25, 0xc000
	ds_read_b128 v[180:183], v151
	ds_read_b128 v[184:187], v151 offset:1024
	ds_read_b128 v[188:191], v151 offset:2048
	ds_read_b128 v[192:195], v151 offset:3072
	ds_read_b128 v[196:199], v151 offset:4096
	ds_read_b128 v[200:203], v151 offset:5120
	ds_read_b128 v[204:207], v151 offset:6144
	ds_read_b128 v[208:211], v151 offset:7168
	global_load_lds_dwordx4 v[212:213], off
	v_lshl_add_u64 v[212:213], s[14:15], 0, v[142:143]
	s_add_i32 m0, s25, 0xe000
	s_nop 0
	global_load_lds_dwordx4 v[212:213], off
	s_waitcnt lgkmcnt(8)
	s_barrier
	s_waitcnt lgkmcnt(0)
	s_waitcnt lgkmcnt(0)
	v_mfma_f32_16x16x32_bf16 v[126:129], v[144:147], v[180:183], v[126:129]
	v_mfma_f32_16x16x32_bf16 v[118:121], v[156:159], v[180:183], v[118:121]
	v_mfma_f32_16x16x32_bf16 v[110:113], v[144:147], v[188:191], v[110:113]
	v_mfma_f32_16x16x32_bf16 v[102:105], v[156:159], v[188:191], v[102:105]
	v_mfma_f32_16x16x32_bf16 v[94:97], v[144:147], v[196:199], v[94:97]
	v_mfma_f32_16x16x32_bf16 v[86:89], v[156:159], v[196:199], v[86:89]
	v_mfma_f32_16x16x32_bf16 v[78:81], v[144:147], v[204:207], v[78:81]
	v_mfma_f32_16x16x32_bf16 v[70:73], v[156:159], v[204:207], v[70:73]
	v_mfma_f32_16x16x32_bf16 v[126:129], v[152:155], v[184:187], v[126:129]
	v_mfma_f32_16x16x32_bf16 v[118:121], v[176:179], v[184:187], v[118:121]
	v_mfma_f32_16x16x32_bf16 v[110:113], v[152:155], v[192:195], v[110:113]
	v_mfma_f32_16x16x32_bf16 v[102:105], v[176:179], v[192:195], v[102:105]
	v_mfma_f32_16x16x32_bf16 v[94:97], v[152:155], v[200:203], v[94:97]
	v_mfma_f32_16x16x32_bf16 v[86:89], v[176:179], v[200:203], v[86:89]
	v_mfma_f32_16x16x32_bf16 v[78:81], v[152:155], v[208:211], v[78:81]
	v_mfma_f32_16x16x32_bf16 v[70:73], v[176:179], v[208:211], v[70:73]
	s_barrier
	s_add_i32 s50, 0, 0x14000
	s_add_i32 s41, s41, s24
	v_add_u32_e32 v175, s50, v149
	v_lshl_add_u64 v[228:229], s[16:17], 0, v[0:1]
	s_mov_b32 m0, s41
	ds_read_b128 v[212:215], v175
	ds_read_b128 v[216:219], v175 offset:1024
	ds_read_b128 v[220:223], v175 offset:2048
	ds_read_b128 v[224:227], v175 offset:3072
	global_load_lds_dwordx4 v[228:229], off
	v_lshl_add_u64 v[230:231], s[16:17], 0, v[134:135]
	s_add_i32 m0, s41, 0x2000
	s_nop 0
	global_load_lds_dwordx4 v[230:231], off
	s_barrier
	s_waitcnt lgkmcnt(0)
	s_waitcnt lgkmcnt(0)
	v_mfma_f32_16x16x32_bf16 v[122:125], v[212:215], v[180:183], v[122:125]
	v_mfma_f32_16x16x32_bf16 v[114:117], v[220:223], v[180:183], v[114:117]
	v_mfma_f32_16x16x32_bf16 v[106:109], v[212:215], v[188:191], v[106:109]
	v_mfma_f32_16x16x32_bf16 v[98:101], v[220:223], v[188:191], v[98:101]
	v_mfma_f32_16x16x32_bf16 v[90:93], v[212:215], v[196:199], v[90:93]
	v_mfma_f32_16x16x32_bf16 v[82:85], v[220:223], v[196:199], v[82:85]
	v_mfma_f32_16x16x32_bf16 v[74:77], v[212:215], v[204:207], v[74:77]
	v_mfma_f32_16x16x32_bf16 v[66:69], v[220:223], v[204:207], v[66:69]
	v_mfma_f32_16x16x32_bf16 v[122:125], v[216:219], v[184:187], v[122:125]
	v_mfma_f32_16x16x32_bf16 v[114:117], v[224:227], v[184:187], v[114:117]
	v_mfma_f32_16x16x32_bf16 v[106:109], v[216:219], v[192:195], v[106:109]
	v_mfma_f32_16x16x32_bf16 v[98:101], v[224:227], v[192:195], v[98:101]
	v_mfma_f32_16x16x32_bf16 v[90:93], v[216:219], v[200:203], v[90:93]
	v_mfma_f32_16x16x32_bf16 v[82:85], v[224:227], v[200:203], v[82:85]
	v_mfma_f32_16x16x32_bf16 v[74:77], v[216:219], v[208:211], v[74:77]
	v_mfma_f32_16x16x32_bf16 v[66:69], v[224:227], v[208:211], v[66:69]
	s_mov_b32 m0, s25
	v_lshl_add_u64 v[232:233], s[18:19], 0, v[138:139]
	s_barrier
	ds_read_b128 v[180:183], v151 offset:16384
	ds_read_b128 v[184:187], v151 offset:17408
	ds_read_b128 v[188:191], v151 offset:18432
	ds_read_b128 v[192:195], v151 offset:19456
	ds_read_b128 v[196:199], v151 offset:20480
	ds_read_b128 v[200:203], v151 offset:21504
	ds_read_b128 v[204:207], v151 offset:22528
	ds_read_b128 v[208:211], v151 offset:23552
	global_load_lds_dwordx4 v[232:233], off
	v_lshl_add_u64 v[234:235], s[18:19], 0, v[136:137]
	s_mov_b32 m0, s26
	s_nop 0
	global_load_lds_dwordx4 v[234:235], off
	s_barrier
	s_waitcnt lgkmcnt(0)
	s_waitcnt lgkmcnt(0)
	v_mfma_f32_16x16x32_bf16 v[62:65], v[144:147], v[180:183], v[62:65]
	v_mfma_f32_16x16x32_bf16 v[54:57], v[156:159], v[180:183], v[54:57]
	v_mfma_f32_16x16x32_bf16 v[46:49], v[144:147], v[188:191], v[46:49]
	v_mfma_f32_16x16x32_bf16 v[38:41], v[156:159], v[188:191], v[38:41]
	v_mfma_f32_16x16x32_bf16 v[30:33], v[144:147], v[196:199], v[30:33]
	v_mfma_f32_16x16x32_bf16 v[22:25], v[156:159], v[196:199], v[22:25]
	v_mfma_f32_16x16x32_bf16 v[14:17], v[144:147], v[204:207], v[14:17]
	v_mfma_f32_16x16x32_bf16 v[6:9], v[156:159], v[204:207], v[6:9]
	v_mfma_f32_16x16x32_bf16 v[62:65], v[152:155], v[184:187], v[62:65]
	v_mfma_f32_16x16x32_bf16 v[54:57], v[176:179], v[184:187], v[54:57]
	v_mfma_f32_16x16x32_bf16 v[46:49], v[152:155], v[192:195], v[46:49]
	v_mfma_f32_16x16x32_bf16 v[38:41], v[176:179], v[192:195], v[38:41]
	v_mfma_f32_16x16x32_bf16 v[30:33], v[152:155], v[200:203], v[30:33]
	v_mfma_f32_16x16x32_bf16 v[22:25], v[176:179], v[200:203], v[22:25]
	v_mfma_f32_16x16x32_bf16 v[14:17], v[152:155], v[208:211], v[14:17]
	v_mfma_f32_16x16x32_bf16 v[6:9], v[176:179], v[208:211], v[6:9]
	s_barrier
; #define PG8_STAGE(bufoff, gbase, voff) do { _Pragma("unroll") for (int _i = 0; _i < 2; ++_i) \
;         __builtin_amdgcn_global_load_lds((const unsigned*)((const char*)(gbase) + (voff)[_i]), (PG8_LAS unsigned*)(lds + (bufoff) + ldsw + _i * 8192), 16, 0, 0); } while (0)
; #define PG8_LDA(dst, b, h) do { _Pragma("unroll") for (int m = 0; m < 4; ++m) _Pragma("unroll") for (int k = 0; k < 2; ++k) dst[m][k] = *(const PG8_LAS bf16x8*)(lds + PG8_SA(b, h) + aoff + m * 2048 + k * 1024); } while (0)
; #define PG8_LDB(dst, b, h) do { _Pragma("unroll") for (int n = 0; n < 2; ++n) _Pragma("unroll") for (int k = 0; k < 2; ++k) dst[n][k] = *(const PG8_LAS bf16x8*)(lds + PG8_SB(b, h) + boff + n * 2048 + k * 1024); } while (0)
; #define PG8_MMA(ai, bj, At, Bt) do { __builtin_amdgcn_s_setprio(1); _Pragma("unroll") for (int m = 0; m < 4; ++m) _Pragma("unroll") for (int n = 0; n < 2; ++n) _Pragma("unroll") for (int k = 0; k < 2; ++k) \
;         acc[ai][bj][m][n] = __builtin_amdgcn_mfma_f32_16x16x32_bf16(Bt[n][k], At[m][k], acc[ai][bj][m][n], 0, 0, 0); __builtin_amdgcn_s_setprio(0); } while (0)
; #define PG8_WAIT_V(n) asm volatile("s_waitcnt vmcnt(" #n ")" ::: "memory")
; #define PG8_WAIT_L(n) asm volatile("s_waitcnt lgkmcnt(" #n ")" ::: "memory")
; #define PG8_BAR __builtin_amdgcn_s_barrier()
; #define PG8_SCHED __builtin_amdgcn_sched_barrier(0)
; template <class Epi, class Sched>
; __device__ __forceinline__ void gemm_phase(PG8_LAS unsigned char* lds, const Gemm g, const Sched& S, const Epi& E) {
;     ...
;             PG8_STAGE(PG8_SB(0, 1), b2 + hstep, voffB);
;             PG8_WAIT_V(6); PG8_BAR; PG8_MMA(1, 1, At, B1); PG8_BAR;
;             PG8_LDB(B0, 1, 0); PG8_SCHED; PG8_LDA(At, 1, 0); PG8_STAGE(PG8_SA(0, 1), a2 + hstep, voffA);
;             PG8_WAIT_L(8); PG8_BAR; PG8_WAIT_L(0); PG8_MMA(0, 0, At, B0); PG8_BAR; PG8_SCHED;
;             PG8_LDB(B1, 1, 1); PG8_STAGE(PG8_SB(1, 0), b3, voffB);
;             PG8_BAR; PG8_WAIT_L(0); PG8_MMA(0, 1, At, B1); PG8_BAR;
;             PG8_LDA(At, 1, 1); PG8_STAGE(PG8_SA(1, 0), a3, voffA);
	s_add_u32 s44, s16, 0x40000
	s_addc_u32 s45, s17, 0
	s_add_i32 s41, s50, s24
	v_lshl_add_u64 v[144:145], s[44:45], 0, v[0:1]
	s_mov_b32 m0, s41
	s_nop 0
	global_load_lds_dwordx4 v[144:145], off
	v_lshl_add_u64 v[144:145], s[44:45], 0, v[134:135]
	s_add_i32 m0, s41, 0x2000
	s_nop 0
	global_load_lds_dwordx4 v[144:145], off
	s_waitcnt vmcnt(6)
	s_barrier
	v_mfma_f32_16x16x32_bf16 v[58:61], v[212:215], v[180:183], v[58:61]
	v_mfma_f32_16x16x32_bf16 v[50:53], v[220:223], v[180:183], v[50:53]
	v_mfma_f32_16x16x32_bf16 v[42:45], v[212:215], v[188:191], v[42:45]
	v_mfma_f32_16x16x32_bf16 v[34:37], v[220:223], v[188:191], v[34:37]
	v_mfma_f32_16x16x32_bf16 v[26:29], v[212:215], v[196:199], v[26:29]
	v_mfma_f32_16x16x32_bf16 v[18:21], v[220:223], v[196:199], v[18:21]
	v_mfma_f32_16x16x32_bf16 v[10:13], v[212:215], v[204:207], v[10:13]
	v_mfma_f32_16x16x32_bf16 v[2:5], v[220:223], v[204:207], v[2:5]
	v_mfma_f32_16x16x32_bf16 v[58:61], v[216:219], v[184:187], v[58:61]
	v_mfma_f32_16x16x32_bf16 v[50:53], v[224:227], v[184:187], v[50:53]
	v_mfma_f32_16x16x32_bf16 v[42:45], v[216:219], v[192:195], v[42:45]
	v_mfma_f32_16x16x32_bf16 v[34:37], v[224:227], v[192:195], v[34:37]
	v_mfma_f32_16x16x32_bf16 v[26:29], v[216:219], v[200:203], v[26:29]
	v_mfma_f32_16x16x32_bf16 v[18:21], v[224:227], v[200:203], v[18:21]
	v_mfma_f32_16x16x32_bf16 v[10:13], v[216:219], v[208:211], v[10:13]
	v_mfma_f32_16x16x32_bf16 v[2:5], v[224:227], v[208:211], v[2:5]
	s_add_i32 s41, 0, 0x18000
	v_add_u32_e32 v175, s41, v149
	s_barrier
	ds_read_b128 v[144:147], v175
	ds_read_b128 v[152:155], v175 offset:1024
	ds_read_b128 v[156:159], v175 offset:2048
	ds_read_b128 v[176:179], v175 offset:3072
	s_add_u32 s18, s18, 0x40000
	s_addc_u32 s19, s19, 0
	s_mov_b32 m0, s27
	v_lshl_add_u64 v[212:213], s[18:19], 0, v[138:139]
	ds_read_b128 v[180:183], v151 offset:32768
	ds_read_b128 v[184:187], v151 offset:33792
	ds_read_b128 v[188:191], v151 offset:34816
	ds_read_b128 v[192:195], v151 offset:35840
	ds_read_b128 v[196:199], v151 offset:36864
	ds_read_b128 v[200:203], v151 offset:37888
	ds_read_b128 v[204:207], v151 offset:38912
	ds_read_b128 v[208:211], v151 offset:39936
	global_load_lds_dwordx4 v[212:213], off
	v_lshl_add_u64 v[212:213], s[18:19], 0, v[136:137]
	s_mov_b32 m0, s28
	s_nop 0
	global_load_lds_dwordx4 v[212:213], off
	s_waitcnt lgkmcnt(8)
	s_barrier
	s_waitcnt lgkmcnt(0)
	s_waitcnt lgkmcnt(0)
	v_mfma_f32_16x16x32_bf16 v[126:129], v[144:147], v[180:183], v[126:129]
	v_mfma_f32_16x16x32_bf16 v[118:121], v[156:159], v[180:183], v[118:121]
	v_mfma_f32_16x16x32_bf16 v[110:113], v[144:147], v[188:191], v[110:113]
	v_mfma_f32_16x16x32_bf16 v[102:105], v[156:159], v[188:191], v[102:105]
	v_mfma_f32_16x16x32_bf16 v[94:97], v[144:147], v[196:199], v[94:97]
	v_mfma_f32_16x16x32_bf16 v[86:89], v[156:159], v[196:199], v[86:89]
	v_mfma_f32_16x16x32_bf16 v[78:81], v[144:147], v[204:207], v[78:81]
	v_mfma_f32_16x16x32_bf16 v[70:73], v[156:159], v[204:207], v[70:73]
	v_mfma_f32_16x16x32_bf16 v[126:129], v[152:155], v[184:187], v[126:129]
	v_mfma_f32_16x16x32_bf16 v[118:121], v[176:179], v[184:187], v[118:121]
	v_mfma_f32_16x16x32_bf16 v[110:113], v[152:155], v[192:195], v[110:113]
	v_mfma_f32_16x16x32_bf16 v[102:105], v[176:179], v[192:195], v[102:105]
	v_mfma_f32_16x16x32_bf16 v[94:97], v[152:155], v[200:203], v[94:97]
	v_mfma_f32_16x16x32_bf16 v[86:89], v[176:179], v[200:203], v[86:89]
	v_mfma_f32_16x16x32_bf16 v[78:81], v[152:155], v[208:211], v[78:81]
	v_mfma_f32_16x16x32_bf16 v[70:73], v[176:179], v[208:211], v[70:73]
	s_barrier
	s_add_i32 s18, 0, 0x1c000
	s_add_i32 s19, s41, s24
	v_add_u32_e32 v175, s18, v149
	v_lshl_add_u64 v[228:229], v[228:229], 0, s[70:71]
	s_mov_b32 m0, s19
	ds_read_b128 v[212:215], v175
	ds_read_b128 v[216:219], v175 offset:1024
	ds_read_b128 v[220:223], v175 offset:2048
	ds_read_b128 v[224:227], v175 offset:3072
	global_load_lds_dwordx4 v[228:229], off
	v_lshl_add_u64 v[228:229], v[230:231], 0, s[70:71]
	s_add_i32 m0, s19, 0x2000
	s_nop 0
	global_load_lds_dwordx4 v[228:229], off
	s_barrier
	s_waitcnt lgkmcnt(0)
	s_waitcnt lgkmcnt(0)
	v_mfma_f32_16x16x32_bf16 v[122:125], v[212:215], v[180:183], v[122:125]
	v_mfma_f32_16x16x32_bf16 v[114:117], v[220:223], v[180:183], v[114:117]
	v_mfma_f32_16x16x32_bf16 v[106:109], v[212:215], v[188:191], v[106:109]
	v_mfma_f32_16x16x32_bf16 v[98:101], v[220:223], v[188:191], v[98:101]
	v_mfma_f32_16x16x32_bf16 v[90:93], v[212:215], v[196:199], v[90:93]
	v_mfma_f32_16x16x32_bf16 v[82:85], v[220:223], v[196:199], v[82:85]
	v_mfma_f32_16x16x32_bf16 v[74:77], v[212:215], v[204:207], v[74:77]
	v_mfma_f32_16x16x32_bf16 v[66:69], v[220:223], v[204:207], v[66:69]
	v_mfma_f32_16x16x32_bf16 v[122:125], v[216:219], v[184:187], v[122:125]
	v_mfma_f32_16x16x32_bf16 v[114:117], v[224:227], v[184:187], v[114:117]
	v_mfma_f32_16x16x32_bf16 v[106:109], v[216:219], v[192:195], v[106:109]
	v_mfma_f32_16x16x32_bf16 v[98:101], v[224:227], v[192:195], v[98:101]
	v_mfma_f32_16x16x32_bf16 v[90:93], v[216:219], v[200:203], v[90:93]
	v_mfma_f32_16x16x32_bf16 v[82:85], v[224:227], v[200:203], v[82:85]
	v_mfma_f32_16x16x32_bf16 v[74:77], v[216:219], v[208:211], v[74:77]
	v_mfma_f32_16x16x32_bf16 v[66:69], v[224:227], v[208:211], v[66:69]
	s_mov_b32 m0, s29
	v_lshl_add_u64 v[228:229], v[232:233], 0, s[70:71]
	s_barrier
	ds_read_b128 v[180:183], v151 offset:49152
	ds_read_b128 v[184:187], v151 offset:50176
	ds_read_b128 v[188:191], v151 offset:51200
	ds_read_b128 v[192:195], v151 offset:52224
	ds_read_b128 v[196:199], v151 offset:53248
	ds_read_b128 v[200:203], v151 offset:54272
	ds_read_b128 v[204:207], v151 offset:55296
	ds_read_b128 v[208:211], v151 offset:56320
	global_load_lds_dwordx4 v[228:229], off
	v_lshl_add_u64 v[228:229], v[234:235], 0, s[70:71]
	s_mov_b32 m0, s30
	s_nop 0
	global_load_lds_dwordx4 v[228:229], off
	s_barrier
; #define PG8_STAGE(bufoff, gbase, voff) do { _Pragma("unroll") for (int _i = 0; _i < 2; ++_i) \
;         __builtin_amdgcn_global_load_lds((const unsigned*)((const char*)(gbase) + (voff)[_i]), (PG8_LAS unsigned*)(lds + (bufoff) + ldsw + _i * 8192), 16, 0, 0); } while (0)
; #define PG8_LDA(dst, b, h) do { _Pragma("unroll") for (int m = 0; m < 4; ++m) _Pragma("unroll") for (int k = 0; k < 2; ++k) dst[m][k] = *(const PG8_LAS bf16x8*)(lds + PG8_SA(b, h) + aoff + m * 2048 + k * 1024); } while (0)
; #define PG8_MMA(ai, bj, At, Bt) do { __builtin_amdgcn_s_setprio(1); _Pragma("unroll") for (int m = 0; m < 4; ++m) _Pragma("unroll") for (int n = 0; n < 2; ++n) _Pragma("unroll") for (int k = 0; k < 2; ++k) \
;         acc[ai][bj][m][n] = __builtin_amdgcn_mfma_f32_16x16x32_bf16(Bt[n][k], At[m][k], acc[ai][bj][m][n], 0, 0, 0); __builtin_amdgcn_s_setprio(0); } while (0)
; #define PG8_WAIT_V(n) asm volatile("s_waitcnt vmcnt(" #n ")" ::: "memory")
; #define PG8_WAIT_L(n) asm volatile("s_waitcnt lgkmcnt(" #n ")" ::: "memory")
; #define PG8_BAR __builtin_amdgcn_s_barrier()
; template <class Epi, class Sched>
; __device__ __forceinline__ void gemm_phase(PG8_LAS unsigned char* lds, const Gemm g, const Sched& S, const Epi& E) {
;     ...
;             PG8_LDA(At, 1, 1); PG8_STAGE(PG8_SA(1, 0), a3, voffA);
;             PG8_BAR; PG8_WAIT_L(0); PG8_MMA(1, 0, At, B0); PG8_BAR; PG8_SCHED;
;             PG8_STAGE(PG8_SB(1, 1), b3 + hstep, voffB);
;             PG8_WAIT_V(6); PG8_BAR; PG8_MMA(1, 1, At, B1); PG8_BAR;
;     __device__ __forceinline__ void operator()(const f32x4 (&acc)[2][2][4][2], const pg8::Unit& u, int wr, int wc, int fr, int fq) const {
;         const int row0 = u.pm * 256 + wr * 64 + fr, col0 = u.pn * 128 + wc * 32 + 8 * fq;
; #pragma unroll
;         for (int ai = 0; ai < 2; ++ai)
; #pragma unroll
;             for (int m = 0; m < 4; ++m) {
;                 bf16_t* p = O + (size_t)(row0 + ai * 128 + m * 16) * FF + col0;
;                 const f32x4 g0 = acc[ai][0][m][0], g1 = acc[ai][0][m][1], u0 = acc[ai][1][m][0], u1 = acc[ai][1][m][1];
;                 u32x4 w;
;                 w.x = pk2(silu(g0[0]) * u0[0], silu(g0[1]) * u0[1]); w.y = pk2(silu(g0[2]) * u0[2], silu(g0[3]) * u0[3]);
;                 w.z = pk2(silu(g1[0]) * u1[0], silu(g1[1]) * u1[1]); w.w = pk2(silu(g1[2]) * u1[2], silu(g1[3]) * u1[3]);
;                 *(u32x4*)p = w;
;             }
	s_waitcnt lgkmcnt(0)
	s_waitcnt lgkmcnt(0)
	v_mfma_f32_16x16x32_bf16 v[62:65], v[144:147], v[180:183], v[62:65]
	v_mfma_f32_16x16x32_bf16 v[54:57], v[156:159], v[180:183], v[54:57]
	v_mfma_f32_16x16x32_bf16 v[46:49], v[144:147], v[188:191], v[46:49]
	v_mfma_f32_16x16x32_bf16 v[38:41], v[156:159], v[188:191], v[38:41]
	v_mfma_f32_16x16x32_bf16 v[30:33], v[144:147], v[196:199], v[30:33]
	v_mfma_f32_16x16x32_bf16 v[22:25], v[156:159], v[196:199], v[22:25]
	v_mfma_f32_16x16x32_bf16 v[14:17], v[144:147], v[204:207], v[14:17]
	v_mfma_f32_16x16x32_bf16 v[6:9], v[156:159], v[204:207], v[6:9]
	v_mfma_f32_16x16x32_bf16 v[62:65], v[152:155], v[184:187], v[62:65]
	v_mfma_f32_16x16x32_bf16 v[54:57], v[176:179], v[184:187], v[54:57]
	v_mfma_f32_16x16x32_bf16 v[46:49], v[152:155], v[192:195], v[46:49]
	v_mfma_f32_16x16x32_bf16 v[38:41], v[176:179], v[192:195], v[38:41]
	v_mfma_f32_16x16x32_bf16 v[30:33], v[152:155], v[200:203], v[30:33]
	v_mfma_f32_16x16x32_bf16 v[22:25], v[176:179], v[200:203], v[22:25]
	v_mfma_f32_16x16x32_bf16 v[14:17], v[152:155], v[208:211], v[14:17]
	v_mfma_f32_16x16x32_bf16 v[6:9], v[176:179], v[208:211], v[6:9]
	s_barrier
	s_add_u32 s16, s16, 0x40080
	s_addc_u32 s17, s17, 0
	s_add_i32 s18, s18, s24
	v_lshl_add_u64 v[144:145], s[16:17], 0, v[0:1]
	s_mov_b32 m0, s18
	s_nop 0
	global_load_lds_dwordx4 v[144:145], off
	v_lshl_add_u64 v[144:145], s[16:17], 0, v[134:135]
	s_add_i32 m0, s18, 0x2000
	s_nop 0
	global_load_lds_dwordx4 v[144:145], off
	s_waitcnt vmcnt(6)
	s_barrier
	v_mfma_f32_16x16x32_bf16 v[58:61], v[212:215], v[180:183], v[58:61]
	v_mfma_f32_16x16x32_bf16 v[50:53], v[220:223], v[180:183], v[50:53]
	v_mfma_f32_16x16x32_bf16 v[42:45], v[212:215], v[188:191], v[42:45]
	v_mfma_f32_16x16x32_bf16 v[34:37], v[220:223], v[188:191], v[34:37]
	v_mfma_f32_16x16x32_bf16 v[26:29], v[212:215], v[196:199], v[26:29]
	v_mfma_f32_16x16x32_bf16 v[18:21], v[220:223], v[196:199], v[18:21]
	v_mfma_f32_16x16x32_bf16 v[10:13], v[212:215], v[204:207], v[10:13]
	v_mfma_f32_16x16x32_bf16 v[2:5], v[220:223], v[204:207], v[2:5]
	v_mfma_f32_16x16x32_bf16 v[58:61], v[216:219], v[184:187], v[58:61]
	v_mfma_f32_16x16x32_bf16 v[50:53], v[224:227], v[184:187], v[50:53]
	v_mfma_f32_16x16x32_bf16 v[42:45], v[216:219], v[192:195], v[42:45]
	v_mfma_f32_16x16x32_bf16 v[34:37], v[224:227], v[192:195], v[34:37]
	v_mfma_f32_16x16x32_bf16 v[26:29], v[216:219], v[200:203], v[26:29]
	v_mfma_f32_16x16x32_bf16 v[18:21], v[224:227], v[200:203], v[18:21]
	v_mfma_f32_16x16x32_bf16 v[10:13], v[216:219], v[208:211], v[10:13]
	v_mfma_f32_16x16x32_bf16 v[2:5], v[224:227], v[208:211], v[2:5]
	s_add_i32 s40, s40, 2
	s_add_u32 s14, s14, 0x100
	s_addc_u32 s15, s15, 0
	s_add_u32 s38, s38, 0x100
	s_addc_u32 s39, s39, 0
	s_cmp_gt_u32 s40, 13
	s_barrier
	s_cbranch_scc0 .LBB0_1129
	v_mul_f32_e32 v153, 0xbfb8aa3b, v126
	v_exp_f32_e32 v153, v153
	v_lshl_or_b32 v146, s34, 7, v150
	v_lshl_add_u32 v152, s35, 8, v148
	v_ashrrev_i32_e32 v147, 31, v146
	v_add_f32_e32 v153, 1.0, v153
	v_rcp_f32_e32 v153, v153
	v_mov_b64_e32 v[144:145], s[0:1]
	v_mad_i64_i32 v[154:155], s[14:15], v152, s52, v[144:145]
	v_mul_f32_e32 v126, v126, v153
	v_mul_f32_e32 v122, v126, v122
	v_mul_f32_e32 v126, 0xbfb8aa3b, v127
	v_exp_f32_e32 v126, v126
	v_lshlrev_b64 v[146:147], 1, v[146:147]
	v_lshl_add_u64 v[154:155], v[154:155], 0, v[146:147]
	s_and_b64 vcc, exec, s[4:5]
	v_add_f32_e32 v126, 1.0, v126
	v_rcp_f32_e32 v126, v126
	s_mov_b32 s34, s6
	s_mov_b32 s35, s8
	s_mov_b64 s[16:17], s[12:13]
	v_mul_f32_e32 v126, v127, v126
	v_mul_f32_e32 v123, v126, v123
	v_cvt_pk_bf16_f32 v122, v122, v123
	v_mul_f32_e32 v123, 0xbfb8aa3b, v128
	v_exp_f32_e32 v123, v123
	s_nop 0
	v_add_f32_e32 v123, 1.0, v123
	v_rcp_f32_e32 v123, v123
	s_nop 0
	v_mul_f32_e32 v123, v128, v123
	v_mul_f32_e32 v123, v123, v124
	v_mul_f32_e32 v124, 0xbfb8aa3b, v129
	v_exp_f32_e32 v124, v124
	s_nop 0
	v_add_f32_e32 v124, 1.0, v124
	v_rcp_f32_e32 v124, v124
	s_nop 0
	v_mul_f32_e32 v124, v129, v124
	v_mul_f32_e32 v124, v124, v125
	v_cvt_pk_bf16_f32 v123, v123, v124
	v_mul_f32_e32 v124, 0xbfb8aa3b, v118
	v_exp_f32_e32 v124, v124
	s_nop 0
	v_add_f32_e32 v124, 1.0, v124
	v_rcp_f32_e32 v124, v124
	s_nop 0
	v_mul_f32_e32 v118, v118, v124
	v_mul_f32_e32 v114, v118, v114
	v_mul_f32_e32 v118, 0xbfb8aa3b, v119
	v_exp_f32_e32 v118, v118
	s_nop 0
	v_add_f32_e32 v118, 1.0, v118
	v_rcp_f32_e32 v118, v118
	s_nop 0
	v_mul_f32_e32 v118, v119, v118
	v_mul_f32_e32 v115, v118, v115
	v_cvt_pk_bf16_f32 v124, v114, v115
	v_mul_f32_e32 v114, 0xbfb8aa3b, v120
	v_exp_f32_e32 v114, v114
	v_mul_f32_e32 v115, 0xbfb8aa3b, v121
	v_exp_f32_e32 v115, v115
	v_add_f32_e32 v114, 1.0, v114
	v_rcp_f32_e32 v114, v114
	v_add_f32_e32 v115, 1.0, v115
	v_rcp_f32_e32 v115, v115
	v_mul_f32_e32 v114, v120, v114
	v_mul_f32_e32 v114, v114, v116
	v_mul_f32_e32 v116, 0xbfb8aa3b, v110
	v_exp_f32_e32 v116, v116
	v_mul_f32_e32 v115, v121, v115
	v_mul_f32_e32 v115, v115, v117
	v_cvt_pk_bf16_f32 v125, v114, v115
	v_add_f32_e32 v116, 1.0, v116
	v_rcp_f32_e32 v116, v116
	global_store_dwordx4 v[154:155], v[122:125], off
	v_or_b32_e32 v114, 16, v152
	v_mad_i64_i32 v[114:115], s[14:15], v114, s52, v[144:145]
	v_mul_f32_e32 v110, v110, v116
	v_mul_f32_e32 v106, v110, v106
	v_mul_f32_e32 v110, 0xbfb8aa3b, v111
	v_exp_f32_e32 v110, v110
	v_lshl_add_u64 v[114:115], v[114:115], 0, v[146:147]
	v_add_f32_e32 v110, 1.0, v110
	v_rcp_f32_e32 v110, v110
	s_nop 0
	v_mul_f32_e32 v110, v111, v110
	v_mul_f32_e32 v107, v110, v107
	v_cvt_pk_bf16_f32 v106, v106, v107
	v_mul_f32_e32 v107, 0xbfb8aa3b, v112
	v_exp_f32_e32 v107, v107
	s_nop 0
	v_add_f32_e32 v107, 1.0, v107
	v_rcp_f32_e32 v107, v107
	s_nop 0
	v_mul_f32_e32 v107, v112, v107
; __device__ __forceinline__ unsigned pk2(float lo, float hi) { return pg8::cvt_pk_bf16(lo, hi); }
; __device__ __forceinline__ float silu(float x) { return x * __builtin_amdgcn_rcpf(1.0f + __expf(-x)); }
;     __device__ __forceinline__ void operator()(const f32x4 (&acc)[2][2][4][2], const pg8::Unit& u, int wr, int wc, int fr, int fq) const {
;         const int row0 = u.pm * 256 + wr * 64 + fr, col0 = u.pn * 128 + wc * 32 + 8 * fq;
; #pragma unroll
;         for (int ai = 0; ai < 2; ++ai)
; #pragma unroll
;             for (int m = 0; m < 4; ++m) {
;                 bf16_t* p = O + (size_t)(row0 + ai * 128 + m * 16) * FF + col0;
;                 const f32x4 g0 = acc[ai][0][m][0], g1 = acc[ai][0][m][1], u0 = acc[ai][1][m][0], u1 = acc[ai][1][m][1];
;                 u32x4 w;
;                 w.x = pk2(silu(g0[0]) * u0[0], silu(g0[1]) * u0[1]); w.y = pk2(silu(g0[2]) * u0[2], silu(g0[3]) * u0[3]);
;                 w.z = pk2(silu(g1[0]) * u1[0], silu(g1[1]) * u1[1]); w.w = pk2(silu(g1[2]) * u1[2], silu(g1[3]) * u1[3]);
;                 *(u32x4*)p = w;
;             }
	v_mul_f32_e32 v107, v107, v108
	v_mul_f32_e32 v108, 0xbfb8aa3b, v113
	v_exp_f32_e32 v108, v108
	s_nop 0
	v_add_f32_e32 v108, 1.0, v108
	v_rcp_f32_e32 v108, v108
	s_nop 0
	v_mul_f32_e32 v108, v113, v108
	v_mul_f32_e32 v108, v108, v109
	v_cvt_pk_bf16_f32 v107, v107, v108
	v_mul_f32_e32 v108, 0xbfb8aa3b, v102
	v_exp_f32_e32 v108, v108
	s_nop 0
	v_add_f32_e32 v108, 1.0, v108
	v_rcp_f32_e32 v108, v108
	s_nop 0
	v_mul_f32_e32 v102, v102, v108
	v_mul_f32_e32 v98, v102, v98
	v_mul_f32_e32 v102, 0xbfb8aa3b, v103
	v_exp_f32_e32 v102, v102
	s_nop 0
	v_add_f32_e32 v102, 1.0, v102
	v_rcp_f32_e32 v102, v102
	s_nop 0
	v_mul_f32_e32 v102, v103, v102
	v_mul_f32_e32 v99, v102, v99
	v_cvt_pk_bf16_f32 v108, v98, v99
	v_mul_f32_e32 v98, 0xbfb8aa3b, v104
	v_exp_f32_e32 v98, v98
	v_mul_f32_e32 v99, 0xbfb8aa3b, v105
	v_exp_f32_e32 v99, v99
	v_add_f32_e32 v98, 1.0, v98
	v_rcp_f32_e32 v98, v98
	v_add_f32_e32 v99, 1.0, v99
	v_rcp_f32_e32 v99, v99
	v_mul_f32_e32 v98, v104, v98
	v_mul_f32_e32 v98, v98, v100
	v_mul_f32_e32 v100, 0xbfb8aa3b, v94
	v_exp_f32_e32 v100, v100
	v_mul_f32_e32 v99, v105, v99
	v_mul_f32_e32 v99, v99, v101
	v_cvt_pk_bf16_f32 v109, v98, v99
	v_add_f32_e32 v100, 1.0, v100
	v_rcp_f32_e32 v100, v100
	global_store_dwordx4 v[114:115], v[106:109], off
	v_or_b32_e32 v98, 32, v152
	v_mad_i64_i32 v[98:99], s[14:15], v98, s52, v[144:145]
	v_mul_f32_e32 v94, v94, v100
	v_mul_f32_e32 v90, v94, v90
	v_mul_f32_e32 v94, 0xbfb8aa3b, v95
	v_exp_f32_e32 v94, v94
	v_lshl_add_u64 v[98:99], v[98:99], 0, v[146:147]
	v_add_f32_e32 v94, 1.0, v94
	v_rcp_f32_e32 v94, v94
	s_nop 0
	v_mul_f32_e32 v94, v95, v94
	v_mul_f32_e32 v91, v94, v91
	v_cvt_pk_bf16_f32 v90, v90, v91
	v_mul_f32_e32 v91, 0xbfb8aa3b, v96
	v_exp_f32_e32 v91, v91
	s_nop 0
	v_add_f32_e32 v91, 1.0, v91
	v_rcp_f32_e32 v91, v91
	s_nop 0
	v_mul_f32_e32 v91, v96, v91
	v_mul_f32_e32 v91, v91, v92
	v_mul_f32_e32 v92, 0xbfb8aa3b, v97
	v_exp_f32_e32 v92, v92
	s_nop 0
	v_add_f32_e32 v92, 1.0, v92
	v_rcp_f32_e32 v92, v92
	s_nop 0
	v_mul_f32_e32 v92, v97, v92
	v_mul_f32_e32 v92, v92, v93
	v_cvt_pk_bf16_f32 v91, v91, v92
	v_mul_f32_e32 v92, 0xbfb8aa3b, v86
	v_exp_f32_e32 v92, v92
	s_nop 0
	v_add_f32_e32 v92, 1.0, v92
	v_rcp_f32_e32 v92, v92
	s_nop 0
	v_mul_f32_e32 v86, v86, v92
	v_mul_f32_e32 v82, v86, v82
	v_mul_f32_e32 v86, 0xbfb8aa3b, v87
	v_exp_f32_e32 v86, v86
	s_nop 0
	v_add_f32_e32 v86, 1.0, v86
	v_rcp_f32_e32 v86, v86
	s_nop 0
	v_mul_f32_e32 v86, v87, v86
	v_mul_f32_e32 v83, v86, v83
	v_cvt_pk_bf16_f32 v92, v82, v83
	v_mul_f32_e32 v82, 0xbfb8aa3b, v88
	v_exp_f32_e32 v82, v82
	v_mul_f32_e32 v83, 0xbfb8aa3b, v89
	v_exp_f32_e32 v83, v83
	v_add_f32_e32 v82, 1.0, v82
	v_rcp_f32_e32 v82, v82
	v_add_f32_e32 v83, 1.0, v83
	v_rcp_f32_e32 v83, v83
	v_mul_f32_e32 v82, v88, v82
	v_mul_f32_e32 v82, v82, v84
	v_mul_f32_e32 v84, 0xbfb8aa3b, v78
	v_exp_f32_e32 v84, v84
	v_mul_f32_e32 v83, v89, v83
	v_mul_f32_e32 v83, v83, v85
	v_cvt_pk_bf16_f32 v93, v82, v83
	v_add_f32_e32 v84, 1.0, v84
	v_rcp_f32_e32 v84, v84
	global_store_dwordx4 v[98:99], v[90:93], off
	v_or_b32_e32 v82, 48, v152
	v_mad_i64_i32 v[82:83], s[14:15], v82, s52, v[144:145]
	v_mul_f32_e32 v78, v78, v84
	v_mul_f32_e32 v74, v78, v74
	v_mul_f32_e32 v78, 0xbfb8aa3b, v79
	v_exp_f32_e32 v78, v78
	v_lshl_add_u64 v[82:83], v[82:83], 0, v[146:147]
	v_add_f32_e32 v78, 1.0, v78
	v_rcp_f32_e32 v78, v78
	s_nop 0
	v_mul_f32_e32 v78, v79, v78
	v_mul_f32_e32 v75, v78, v75
	v_cvt_pk_bf16_f32 v74, v74, v75
	v_mul_f32_e32 v75, 0xbfb8aa3b, v80
	v_exp_f32_e32 v75, v75
	s_nop 0
	v_add_f32_e32 v75, 1.0, v75
	v_rcp_f32_e32 v75, v75
	s_nop 0
	v_mul_f32_e32 v75, v80, v75
	v_mul_f32_e32 v75, v75, v76
	v_mul_f32_e32 v76, 0xbfb8aa3b, v81
	v_exp_f32_e32 v76, v76
	s_nop 0
	v_add_f32_e32 v76, 1.0, v76
	v_rcp_f32_e32 v76, v76
	s_nop 0
	v_mul_f32_e32 v76, v81, v76
	v_mul_f32_e32 v76, v76, v77
	v_cvt_pk_bf16_f32 v75, v75, v76
	v_mul_f32_e32 v76, 0xbfb8aa3b, v70
	v_exp_f32_e32 v76, v76
	s_nop 0
	v_add_f32_e32 v76, 1.0, v76
	v_rcp_f32_e32 v76, v76
	s_nop 0
	v_mul_f32_e32 v70, v70, v76
	v_mul_f32_e32 v66, v70, v66
	v_mul_f32_e32 v70, 0xbfb8aa3b, v71
	v_exp_f32_e32 v70, v70
	s_nop 0
	v_add_f32_e32 v70, 1.0, v70
	v_rcp_f32_e32 v70, v70
	s_nop 0
	v_mul_f32_e32 v70, v71, v70
	v_mul_f32_e32 v67, v70, v67
	v_cvt_pk_bf16_f32 v76, v66, v67
	v_mul_f32_e32 v66, 0xbfb8aa3b, v72
	v_exp_f32_e32 v66, v66
	v_mul_f32_e32 v67, 0xbfb8aa3b, v73
	v_exp_f32_e32 v67, v67
	v_add_f32_e32 v66, 1.0, v66
	v_rcp_f32_e32 v66, v66
	v_add_f32_e32 v67, 1.0, v67
	v_rcp_f32_e32 v67, v67
	v_mul_f32_e32 v66, v72, v66
	v_mul_f32_e32 v66, v66, v68
	v_mul_f32_e32 v68, 0xbfb8aa3b, v62
	v_exp_f32_e32 v68, v68
	v_mul_f32_e32 v67, v73, v67
	v_mul_f32_e32 v67, v67, v69
	v_cvt_pk_bf16_f32 v77, v66, v67
	v_add_f32_e32 v68, 1.0, v68
	v_rcp_f32_e32 v68, v68
	global_store_dwordx4 v[82:83], v[74:77], off
	v_add_u32_e32 v66, 0x80, v152
	v_mad_i64_i32 v[66:67], s[14:15], v66, s52, v[144:145]
	v_mul_f32_e32 v62, v62, v68
	v_mul_f32_e32 v58, v62, v58
	v_mul_f32_e32 v62, 0xbfb8aa3b, v63
	v_exp_f32_e32 v62, v62
	v_lshl_add_u64 v[66:67], v[66:67], 0, v[146:147]
	v_add_f32_e32 v62, 1.0, v62
	v_rcp_f32_e32 v62, v62
	s_nop 0
	v_mul_f32_e32 v62, v63, v62
	v_mul_f32_e32 v59, v62, v59
	v_cvt_pk_bf16_f32 v58, v58, v59
	v_mul_f32_e32 v59, 0xbfb8aa3b, v64
	v_exp_f32_e32 v59, v59
	s_nop 0
	v_add_f32_e32 v59, 1.0, v59
	v_rcp_f32_e32 v59, v59
	s_nop 0
	v_mul_f32_e32 v59, v64, v59
	v_mul_f32_e32 v59, v59, v60
	v_mul_f32_e32 v60, 0xbfb8aa3b, v65
	v_exp_f32_e32 v60, v60
	s_nop 0
	v_add_f32_e32 v60, 1.0, v60
	v_rcp_f32_e32 v60, v60
	s_nop 0
	v_mul_f32_e32 v60, v65, v60
	v_mul_f32_e32 v60, v60, v61
	v_cvt_pk_bf16_f32 v59, v59, v60
	v_mul_f32_e32 v60, 0xbfb8aa3b, v54
; __device__ __forceinline__ unsigned pk2(float lo, float hi) { return pg8::cvt_pk_bf16(lo, hi); }
; __device__ __forceinline__ float silu(float x) { return x * __builtin_amdgcn_rcpf(1.0f + __expf(-x)); }
; template <class Epi, class Sched>
; __device__ __forceinline__ void gemm_phase(PG8_LAS unsigned char* lds, const Gemm g, const Sched& S, const Epi& E) {
;     ...
;         if constexpr (!Epi::AFTER_DRAIN) { E(acc, cur, wr, wc, fr, fq); S.done(cur); }
;         if (!has_next) break;
;     __device__ __forceinline__ void operator()(const f32x4 (&acc)[2][2][4][2], const pg8::Unit& u, int wr, int wc, int fr, int fq) const {
;         const int row0 = u.pm * 256 + wr * 64 + fr, col0 = u.pn * 128 + wc * 32 + 8 * fq;
; #pragma unroll
;         for (int ai = 0; ai < 2; ++ai)
; #pragma unroll
;             for (int m = 0; m < 4; ++m) {
;                 bf16_t* p = O + (size_t)(row0 + ai * 128 + m * 16) * FF + col0;
;                 const f32x4 g0 = acc[ai][0][m][0], g1 = acc[ai][0][m][1], u0 = acc[ai][1][m][0], u1 = acc[ai][1][m][1];
;                 u32x4 w;
;                 w.x = pk2(silu(g0[0]) * u0[0], silu(g0[1]) * u0[1]); w.y = pk2(silu(g0[2]) * u0[2], silu(g0[3]) * u0[3]);
;                 w.z = pk2(silu(g1[0]) * u1[0], silu(g1[1]) * u1[1]); w.w = pk2(silu(g1[2]) * u1[2], silu(g1[3]) * u1[3]);
;                 *(u32x4*)p = w;
;             }
	v_exp_f32_e32 v60, v60
	s_nop 0
	v_add_f32_e32 v60, 1.0, v60
	v_rcp_f32_e32 v60, v60
	s_nop 0
	v_mul_f32_e32 v54, v54, v60
	v_mul_f32_e32 v50, v54, v50
	v_mul_f32_e32 v54, 0xbfb8aa3b, v55
	v_exp_f32_e32 v54, v54
	s_nop 0
	v_add_f32_e32 v54, 1.0, v54
	v_rcp_f32_e32 v54, v54
	s_nop 0
	v_mul_f32_e32 v54, v55, v54
	v_mul_f32_e32 v51, v54, v51
	v_cvt_pk_bf16_f32 v60, v50, v51
	v_mul_f32_e32 v50, 0xbfb8aa3b, v56
	v_exp_f32_e32 v50, v50
	v_mul_f32_e32 v51, 0xbfb8aa3b, v57
	v_exp_f32_e32 v51, v51
	v_add_f32_e32 v50, 1.0, v50
	v_rcp_f32_e32 v50, v50
	v_add_f32_e32 v51, 1.0, v51
	v_rcp_f32_e32 v51, v51
	v_mul_f32_e32 v50, v56, v50
	v_mul_f32_e32 v50, v50, v52
	v_mul_f32_e32 v52, 0xbfb8aa3b, v46
	v_exp_f32_e32 v52, v52
	v_mul_f32_e32 v51, v57, v51
	v_mul_f32_e32 v51, v51, v53
	v_cvt_pk_bf16_f32 v61, v50, v51
	v_add_f32_e32 v52, 1.0, v52
	v_rcp_f32_e32 v52, v52
	global_store_dwordx4 v[66:67], v[58:61], off
	v_add_u32_e32 v50, 0x90, v152
	v_mad_i64_i32 v[50:51], s[14:15], v50, s52, v[144:145]
	v_mul_f32_e32 v46, v46, v52
	v_mul_f32_e32 v42, v46, v42
	v_mul_f32_e32 v46, 0xbfb8aa3b, v47
	v_exp_f32_e32 v46, v46
	v_lshl_add_u64 v[50:51], v[50:51], 0, v[146:147]
	v_add_f32_e32 v46, 1.0, v46
	v_rcp_f32_e32 v46, v46
	s_nop 0
	v_mul_f32_e32 v46, v47, v46
	v_mul_f32_e32 v43, v46, v43
	v_cvt_pk_bf16_f32 v42, v42, v43
	v_mul_f32_e32 v43, 0xbfb8aa3b, v48
	v_exp_f32_e32 v43, v43
	s_nop 0
	v_add_f32_e32 v43, 1.0, v43
	v_rcp_f32_e32 v43, v43
	s_nop 0
	v_mul_f32_e32 v43, v48, v43
	v_mul_f32_e32 v43, v43, v44
	v_mul_f32_e32 v44, 0xbfb8aa3b, v49
	v_exp_f32_e32 v44, v44
	s_nop 0
	v_add_f32_e32 v44, 1.0, v44
	v_rcp_f32_e32 v44, v44
	s_nop 0
	v_mul_f32_e32 v44, v49, v44
	v_mul_f32_e32 v44, v44, v45
	v_cvt_pk_bf16_f32 v43, v43, v44
	v_mul_f32_e32 v44, 0xbfb8aa3b, v38
	v_exp_f32_e32 v44, v44
	s_nop 0
	v_add_f32_e32 v44, 1.0, v44
	v_rcp_f32_e32 v44, v44
	s_nop 0
	v_mul_f32_e32 v38, v38, v44
	v_mul_f32_e32 v34, v38, v34
	v_mul_f32_e32 v38, 0xbfb8aa3b, v39
	v_exp_f32_e32 v38, v38
	s_nop 0
	v_add_f32_e32 v38, 1.0, v38
	v_rcp_f32_e32 v38, v38
	s_nop 0
	v_mul_f32_e32 v38, v39, v38
	v_mul_f32_e32 v35, v38, v35
	v_cvt_pk_bf16_f32 v44, v34, v35
	v_mul_f32_e32 v34, 0xbfb8aa3b, v40
	v_exp_f32_e32 v34, v34
	v_mul_f32_e32 v35, 0xbfb8aa3b, v41
	v_exp_f32_e32 v35, v35
	v_add_f32_e32 v34, 1.0, v34
	v_rcp_f32_e32 v34, v34
	v_add_f32_e32 v35, 1.0, v35
	v_rcp_f32_e32 v35, v35
	v_mul_f32_e32 v34, v40, v34
	v_mul_f32_e32 v34, v34, v36
	v_mul_f32_e32 v36, 0xbfb8aa3b, v30
	v_exp_f32_e32 v36, v36
	v_mul_f32_e32 v35, v41, v35
	v_mul_f32_e32 v35, v35, v37
	v_cvt_pk_bf16_f32 v45, v34, v35
	v_add_f32_e32 v36, 1.0, v36
	v_rcp_f32_e32 v36, v36
	global_store_dwordx4 v[50:51], v[42:45], off
	v_add_u32_e32 v34, 0xa0, v152
	v_mad_i64_i32 v[34:35], s[14:15], v34, s52, v[144:145]
	v_mul_f32_e32 v30, v30, v36
	v_mul_f32_e32 v26, v30, v26
	v_mul_f32_e32 v30, 0xbfb8aa3b, v31
	v_exp_f32_e32 v30, v30
	v_lshl_add_u64 v[34:35], v[34:35], 0, v[146:147]
	v_add_f32_e32 v30, 1.0, v30
	v_rcp_f32_e32 v30, v30
	s_nop 0
	v_mul_f32_e32 v30, v31, v30
	v_mul_f32_e32 v27, v30, v27
	v_cvt_pk_bf16_f32 v26, v26, v27
	v_mul_f32_e32 v27, 0xbfb8aa3b, v32
	v_exp_f32_e32 v27, v27
	s_nop 0
	v_add_f32_e32 v27, 1.0, v27
	v_rcp_f32_e32 v27, v27
	s_nop 0
	v_mul_f32_e32 v27, v32, v27
	v_mul_f32_e32 v27, v27, v28
	v_mul_f32_e32 v28, 0xbfb8aa3b, v33
	v_exp_f32_e32 v28, v28
	s_nop 0
	v_add_f32_e32 v28, 1.0, v28
	v_rcp_f32_e32 v28, v28
	s_nop 0
	v_mul_f32_e32 v28, v33, v28
	v_mul_f32_e32 v28, v28, v29
	v_cvt_pk_bf16_f32 v27, v27, v28
	v_mul_f32_e32 v28, 0xbfb8aa3b, v22
	v_exp_f32_e32 v28, v28
	s_nop 0
	v_add_f32_e32 v28, 1.0, v28
	v_rcp_f32_e32 v28, v28
	s_nop 0
	v_mul_f32_e32 v22, v22, v28
	v_mul_f32_e32 v18, v22, v18
	v_mul_f32_e32 v22, 0xbfb8aa3b, v23
	v_exp_f32_e32 v22, v22
	s_nop 0
	v_add_f32_e32 v22, 1.0, v22
	v_rcp_f32_e32 v22, v22
	s_nop 0
	v_mul_f32_e32 v22, v23, v22
	v_mul_f32_e32 v19, v22, v19
	v_cvt_pk_bf16_f32 v28, v18, v19
	v_mul_f32_e32 v18, 0xbfb8aa3b, v24
	v_exp_f32_e32 v18, v18
	v_mul_f32_e32 v19, 0xbfb8aa3b, v25
	v_exp_f32_e32 v19, v19
	v_add_f32_e32 v18, 1.0, v18
	v_rcp_f32_e32 v18, v18
	v_add_f32_e32 v19, 1.0, v19
	v_rcp_f32_e32 v19, v19
	v_mul_f32_e32 v18, v24, v18
	v_mul_f32_e32 v18, v18, v20
	v_mul_f32_e32 v20, 0xbfb8aa3b, v14
	v_exp_f32_e32 v20, v20
	v_mul_f32_e32 v19, v25, v19
	v_mul_f32_e32 v19, v19, v21
	v_cvt_pk_bf16_f32 v29, v18, v19
	v_add_f32_e32 v20, 1.0, v20
	v_rcp_f32_e32 v20, v20
	global_store_dwordx4 v[34:35], v[26:29], off
	v_add_u32_e32 v18, 0xb0, v152
	v_mad_i64_i32 v[18:19], s[14:15], v18, s52, v[144:145]
	v_mul_f32_e32 v14, v14, v20
	v_mul_f32_e32 v10, v14, v10
	v_mul_f32_e32 v14, 0xbfb8aa3b, v15
	v_exp_f32_e32 v14, v14
	v_lshl_add_u64 v[18:19], v[18:19], 0, v[146:147]
	s_mov_b64 s[14:15], s[10:11]
	v_add_f32_e32 v14, 1.0, v14
	v_rcp_f32_e32 v14, v14
	s_nop 0
	v_mul_f32_e32 v14, v15, v14
	v_mul_f32_e32 v11, v14, v11
	v_cvt_pk_bf16_f32 v10, v10, v11
	v_mul_f32_e32 v11, 0xbfb8aa3b, v16
	v_exp_f32_e32 v11, v11
	s_nop 0
	v_add_f32_e32 v11, 1.0, v11
	v_rcp_f32_e32 v11, v11
	s_nop 0
	v_mul_f32_e32 v11, v16, v11
	v_mul_f32_e32 v11, v11, v12
	v_mul_f32_e32 v12, 0xbfb8aa3b, v17
	v_exp_f32_e32 v12, v12
	s_nop 0
	v_add_f32_e32 v12, 1.0, v12
	v_rcp_f32_e32 v12, v12
	s_nop 0
	v_mul_f32_e32 v12, v17, v12
	v_mul_f32_e32 v12, v12, v13
	v_cvt_pk_bf16_f32 v11, v11, v12
	v_mul_f32_e32 v12, 0xbfb8aa3b, v6
	v_exp_f32_e32 v12, v12
	s_nop 0
	v_add_f32_e32 v12, 1.0, v12
	v_rcp_f32_e32 v12, v12
	s_nop 0
	v_mul_f32_e32 v6, v6, v12
	v_mul_f32_e32 v2, v6, v2
	v_mul_f32_e32 v6, 0xbfb8aa3b, v7
	v_exp_f32_e32 v6, v6
	s_nop 0
	v_add_f32_e32 v6, 1.0, v6
	v_rcp_f32_e32 v6, v6
	s_nop 0
	v_mul_f32_e32 v6, v7, v6
	v_mul_f32_e32 v3, v6, v3
	v_cvt_pk_bf16_f32 v12, v2, v3
	v_mul_f32_e32 v2, 0xbfb8aa3b, v8
	v_mul_f32_e32 v3, 0xbfb8aa3b, v9
	v_exp_f32_e32 v2, v2
	v_exp_f32_e32 v3, v3
	v_add_f32_e32 v2, 1.0, v2
	v_add_f32_e32 v3, 1.0, v3
	v_rcp_f32_e32 v2, v2
	v_rcp_f32_e32 v3, v3
	v_mul_f32_e32 v2, v8, v2
	v_mul_f32_e32 v3, v9, v3
	v_mul_f32_e32 v2, v2, v4
	v_mul_f32_e32 v3, v3, v5
	v_cvt_pk_bf16_f32 v13, v2, v3
	global_store_dwordx4 v[18:19], v[10:13], off
	s_cbranch_vccz .LBB0_1126
	s_waitcnt vmcnt(0)
	s_cmpk_gt_u32 s2, 0xff
	s_cbranch_scc1 .LBB0_1133
	s_barrier
